# prompt attention: head-invariant bias index and mask flag precomputed once per unit (packed into the jb registers, restored after the head loop); 5 instead of 10 VALU per score element in the head loo
# speedup vs baseline: 1.0065x; 1.0065x over previous
.LBB0_115:
	s_bfe_u32 s24, s22, 0x60001
	s_lshl_b32 s25, s24, 7
	s_and_b32 s23, s22, 1
	s_add_i32 s26, s25, 0xffffff80
	s_ashr_i32 s2, s22, 7
	s_lshl_b32 s88, s23, 7
	v_add_u32_e32 v3, s26, v67
	s_lshl_b32 s3, s2, 13
	v_lshl_add_u64 v[16:17], v[20:21], 0, s[88:89]
	v_cmp_lt_i32_e32 vcc, -1, v3
	v_mov_b32_e32 v6, 0
	v_mov_b32_e32 v2, 0
	v_mov_b32_e32 v8, 0
	v_mov_b32_e32 v9, 0
	v_mov_b32_e32 v10, 0
	v_mov_b32_e32 v11, 0
	v_mov_b32_e32 v12, 0
	v_mov_b32_e32 v13, 0
	v_mov_b32_e32 v14, 0
	v_mov_b32_e32 v15, 0
	s_barrier
	v_add_u32_e32 v238, s26, v67
	v_cmp_lt_i32_e32 vcc, -1, v238
	v_mov_b32_e32 v206, 0
	v_mov_b32_e32 v207, 0
	v_mov_b32_e32 v208, 0
	v_mov_b32_e32 v209, 0
	v_mov_b32_e32 v210, 0
	v_mov_b32_e32 v211, 0
	v_mov_b32_e32 v212, 0
	v_mov_b32_e32 v213, 0
	v_add_u32_e32 v240, s3, v238
	v_ashrrev_i32_e32 v241, 31, v240
	v_lshlrev_b64 v[240:241], 9, v[240:241]
	v_lshl_add_u64 v[240:241], v[16:17], 0, v[240:241]
	s_and_saveexec_b64 s[8:9], vcc
	global_load_dwordx4 v[206:209], v[240:241], off
	global_load_dwordx4 v[210:213], v[240:241], off offset:256
	s_or_b64 exec, exec, s[8:9]
	v_add_u32_e32 v238, s26, v70
	v_cmp_lt_i32_e32 vcc, -1, v238
	v_mov_b32_e32 v214, 0
	v_mov_b32_e32 v215, 0
	v_mov_b32_e32 v216, 0
	v_mov_b32_e32 v217, 0
	v_mov_b32_e32 v218, 0
	v_mov_b32_e32 v219, 0
	v_mov_b32_e32 v220, 0
	v_mov_b32_e32 v221, 0
	v_add_u32_e32 v240, s3, v238
	v_ashrrev_i32_e32 v241, 31, v240
	v_lshlrev_b64 v[240:241], 9, v[240:241]
	v_lshl_add_u64 v[240:241], v[16:17], 0, v[240:241]
	s_and_saveexec_b64 s[8:9], vcc
	global_load_dwordx4 v[214:217], v[240:241], off
	global_load_dwordx4 v[218:221], v[240:241], off offset:256
	s_or_b64 exec, exec, s[8:9]
	v_add_u32_e32 v238, s26, v72
	v_cmp_lt_i32_e32 vcc, -1, v238
	v_mov_b32_e32 v222, 0
	v_mov_b32_e32 v223, 0
	v_mov_b32_e32 v224, 0
	v_mov_b32_e32 v225, 0
	v_mov_b32_e32 v226, 0
	v_mov_b32_e32 v227, 0
	v_mov_b32_e32 v228, 0
	v_mov_b32_e32 v229, 0
	v_add_u32_e32 v240, s3, v238
	v_ashrrev_i32_e32 v241, 31, v240
	v_lshlrev_b64 v[240:241], 9, v[240:241]
	v_lshl_add_u64 v[240:241], v[16:17], 0, v[240:241]
	s_and_saveexec_b64 s[8:9], vcc
	global_load_dwordx4 v[222:225], v[240:241], off
	global_load_dwordx4 v[226:229], v[240:241], off offset:256
	s_or_b64 exec, exec, s[8:9]
	v_add_u32_e32 v238, s26, v74
	v_cmp_lt_i32_e32 vcc, -1, v238
	v_mov_b32_e32 v6, 0
	v_mov_b32_e32 v7, 0
	v_mov_b32_e32 v8, 0
	v_mov_b32_e32 v9, 0
	v_mov_b32_e32 v2, 0
	v_mov_b32_e32 v3, 0
	v_mov_b32_e32 v4, 0
	v_mov_b32_e32 v5, 0
	v_add_u32_e32 v240, s3, v238
	v_ashrrev_i32_e32 v241, 31, v240
	v_lshlrev_b64 v[240:241], 9, v[240:241]
	v_lshl_add_u64 v[240:241], v[16:17], 0, v[240:241]
	s_and_saveexec_b64 s[8:9], vcc
	global_load_dwordx4 v[6:9], v[240:241], off
	global_load_dwordx4 v[2:5], v[240:241], off offset:256
	s_or_b64 exec, exec, s[8:9]
	s_mov_b32 s28, 0
	s_waitcnt vmcnt(7)
	ds_write_b128 v128, v[206:209]
	s_waitcnt vmcnt(6)
	ds_write_b16 v68, v210 offset:36864
	ds_write_b16_d16_hi v68, v210 offset:37392
	ds_write_b16 v68, v211 offset:37920
	ds_write_b16_d16_hi v68, v211 offset:38448
	ds_write_b16 v68, v212 offset:38976
	ds_write_b16_d16_hi v68, v212 offset:39504
	ds_write_b16 v68, v213 offset:40032
	ds_write_b16_d16_hi v68, v213 offset:40560
	s_waitcnt vmcnt(5)
	ds_write_b128 v129, v[214:217]
	s_waitcnt vmcnt(4)
	ds_write_b16 v71, v218 offset:36864
	ds_write_b16_d16_hi v71, v218 offset:37392
	ds_write_b16 v71, v219 offset:37920
	ds_write_b16_d16_hi v71, v219 offset:38448
	ds_write_b16 v71, v220 offset:38976
	ds_write_b16_d16_hi v71, v220 offset:39504
	ds_write_b16 v71, v221 offset:40032
	ds_write_b16_d16_hi v71, v221 offset:40560
	s_waitcnt vmcnt(3)
	ds_write_b128 v130, v[222:225]
	s_waitcnt vmcnt(2)
	ds_write_b16 v73, v226 offset:36864
	ds_write_b16_d16_hi v73, v226 offset:37392
	ds_write_b16 v73, v227 offset:37920
	ds_write_b16_d16_hi v73, v227 offset:38448
	ds_write_b16 v73, v228 offset:38976
	ds_write_b16_d16_hi v73, v228 offset:39504
	ds_write_b16 v73, v229 offset:40032
	ds_write_b16_d16_hi v73, v229 offset:40560
	v_cndmask_b32_e64 v14, 0, 1, s[42:43]
	s_nop 0
	v_readfirstlane_b32 s3, v14
	s_lshl_b32 s3, s3, 3
	s_add_i32 s88, s19, s3
	s_lshl_b64 s[46:47], s[88:89], 2
	s_lshl_b32 s88, s23, 10
	v_add_u32_e32 v10, s88, v204
	v_ashrrev_i32_e32 v11, 31, v10
	v_add_u32_e32 v12, s88, v69
	v_lshl_add_u64 v[10:11], v[10:11], 2, s[0:1]
	v_ashrrev_i32_e32 v13, 31, v12
	v_lshl_add_u64 v[12:13], v[12:13], 2, s[0:1]
	global_load_dword v10, v[10:11], off
	s_nop 0
	global_load_dword v11, v[12:13], off
	s_ashr_i32 s3, s2, 31
	s_lshl_b64 s[2:3], s[2:3], 13
	s_or_b32 s8, s2, s25
	s_mov_b32 s9, s3
	s_waitcnt vmcnt(3)
	ds_write_b128 v131, v[6:9]
	s_waitcnt vmcnt(2)
	ds_write_b16 v75, v2 offset:36864
	ds_write_b16_d16_hi v75, v2 offset:37392
	ds_write_b16 v75, v3 offset:37920
	ds_write_b16_d16_hi v75, v3 offset:38448
	ds_write_b16 v75, v4 offset:38976
	ds_write_b16_d16_hi v75, v4 offset:39504
	ds_write_b16 v75, v5 offset:40032
	ds_write_b16_d16_hi v75, v5 offset:40560
	v_lshl_add_u64 v[6:7], s[8:9], 0, v[22:23]
	v_lshlrev_b64 v[2:3], 11, v[6:7]
	v_lshl_add_u64 v[2:3], s[14:15], 0, v[2:3]
	v_lshl_add_u64 v[2:3], v[2:3], 0, s[88:89]
	v_lshl_add_u64 v[8:9], v[2:3], 0, v[0:1]
	s_lshr_b32 s8, s22, 1
	s_and_b32 s8, s8, 63
	s_lshl_b32 s8, s8, 7
	s_cmp_eq_u32 s24, 0
	s_cselect_b64 s[38:39], -1, 0
	s_or_b32 s2, s2, s8
	v_lshlrev_b64 v[30:31], 10, v[6:7]
	v_lshl_add_u64 v[6:7], s[2:3], 0, v[22:23]
	v_lshlrev_b64 v[6:7], 11, v[6:7]
	v_lshl_or_b32 v6, v14, 10, v6
	v_lshl_add_u64 v[32:33], v[26:27], 0, v[6:7]
	v_lshl_add_u64 v[34:35], v[28:29], 0, v[6:7]
	s_waitcnt vmcnt(1)
	ds_write_b32 v76, v10
	s_waitcnt vmcnt(0)
	ds_write_b32 v77, v11
	s_waitcnt lgkmcnt(0)
	s_barrier
	global_load_dwordx4 v[2:5], v[8:9], off
	global_load_dwordx4 v[10:13], v[8:9], off offset:64
	v_mov_b32_e32 v235, v79
	v_mov_b32_e32 v205, 0x1fc
	v_add_u32_e32 v236, 0x80, v22
	v_cndmask_b32_e64 v237, v195, v22, s[38:39]
	v_sub_u32_e32 v238, v236, v79
	v_sub_u32_e32 v239, v237, v238
	v_or_b32_e32 v239, v239, v238
	v_and_b32_e32 v238, 0x7f, v238
	v_lshlrev_b32_e32 v238, 2, v238
	v_and_b32_e32 v239, 0x80000000, v239
	v_or_b32_e32 v79, v239, v238
	v_sub_u32_e32 v238, v236, v80
	v_sub_u32_e32 v239, v237, v238
	v_or_b32_e32 v239, v239, v238
	v_and_b32_e32 v238, 0x7f, v238
	v_lshlrev_b32_e32 v238, 2, v238
	v_and_b32_e32 v239, 0x80000000, v239
	v_or_b32_e32 v80, v239, v238
	v_sub_u32_e32 v238, v236, v81
	v_sub_u32_e32 v239, v237, v238
	v_or_b32_e32 v239, v239, v238
	v_and_b32_e32 v238, 0x7f, v238
	v_lshlrev_b32_e32 v238, 2, v238
	v_and_b32_e32 v239, 0x80000000, v239
	v_or_b32_e32 v81, v239, v238
	v_sub_u32_e32 v238, v236, v82
	v_sub_u32_e32 v239, v237, v238
	v_or_b32_e32 v239, v239, v238
	v_and_b32_e32 v238, 0x7f, v238
	v_lshlrev_b32_e32 v238, 2, v238
	v_and_b32_e32 v239, 0x80000000, v239
	v_or_b32_e32 v82, v239, v238
	v_sub_u32_e32 v238, v236, v84
	v_sub_u32_e32 v239, v237, v238
	v_or_b32_e32 v239, v239, v238
	v_and_b32_e32 v238, 0x7f, v238
	v_lshlrev_b32_e32 v238, 2, v238
	v_and_b32_e32 v239, 0x80000000, v239
	v_or_b32_e32 v84, v239, v238
	v_sub_u32_e32 v238, v236, v85
	v_sub_u32_e32 v239, v237, v238
	v_or_b32_e32 v239, v239, v238
	v_and_b32_e32 v238, 0x7f, v238
	v_lshlrev_b32_e32 v238, 2, v238
	v_and_b32_e32 v239, 0x80000000, v239
	v_or_b32_e32 v85, v239, v238
	v_sub_u32_e32 v238, v236, v86
	v_sub_u32_e32 v239, v237, v238
	v_or_b32_e32 v239, v239, v238
	v_and_b32_e32 v238, 0x7f, v238
	v_lshlrev_b32_e32 v238, 2, v238
	v_and_b32_e32 v239, 0x80000000, v239
	v_or_b32_e32 v86, v239, v238
	v_sub_u32_e32 v238, v236, v87
	v_sub_u32_e32 v239, v237, v238
	v_or_b32_e32 v239, v239, v238
	v_and_b32_e32 v238, 0x7f, v238
	v_lshlrev_b32_e32 v238, 2, v238
	v_and_b32_e32 v239, 0x80000000, v239
	v_or_b32_e32 v87, v239, v238
	v_sub_u32_e32 v238, v236, v89
	v_sub_u32_e32 v239, v237, v238
	v_or_b32_e32 v239, v239, v238
	v_and_b32_e32 v238, 0x7f, v238
	v_lshlrev_b32_e32 v238, 2, v238
	v_and_b32_e32 v239, 0x80000000, v239
	v_or_b32_e32 v89, v239, v238
	v_sub_u32_e32 v238, v236, v90
	v_sub_u32_e32 v239, v237, v238
	v_or_b32_e32 v239, v239, v238
	v_and_b32_e32 v238, 0x7f, v238
	v_lshlrev_b32_e32 v238, 2, v238
	v_and_b32_e32 v239, 0x80000000, v239
	v_or_b32_e32 v90, v239, v238
	v_sub_u32_e32 v238, v236, v91
	v_sub_u32_e32 v239, v237, v238
	v_or_b32_e32 v239, v239, v238
	v_and_b32_e32 v238, 0x7f, v238
	v_lshlrev_b32_e32 v238, 2, v238
	v_and_b32_e32 v239, 0x80000000, v239
	v_or_b32_e32 v91, v239, v238
	v_sub_u32_e32 v238, v236, v92
	v_sub_u32_e32 v239, v237, v238
	v_or_b32_e32 v239, v239, v238
	v_and_b32_e32 v238, 0x7f, v238
	v_lshlrev_b32_e32 v238, 2, v238
	v_and_b32_e32 v239, 0x80000000, v239
	v_or_b32_e32 v92, v239, v238
	v_sub_u32_e32 v238, v236, v94
	v_sub_u32_e32 v239, v237, v238
	v_or_b32_e32 v239, v239, v238
	v_and_b32_e32 v238, 0x7f, v238
	v_lshlrev_b32_e32 v238, 2, v238
	v_and_b32_e32 v239, 0x80000000, v239
	v_or_b32_e32 v94, v239, v238
	v_sub_u32_e32 v238, v236, v95
	v_sub_u32_e32 v239, v237, v238
	v_or_b32_e32 v239, v239, v238
	v_and_b32_e32 v238, 0x7f, v238
	v_lshlrev_b32_e32 v238, 2, v238
	v_and_b32_e32 v239, 0x80000000, v239
	v_or_b32_e32 v95, v239, v238
	v_sub_u32_e32 v238, v236, v96
	v_sub_u32_e32 v239, v237, v238
	v_or_b32_e32 v239, v239, v238
	v_and_b32_e32 v238, 0x7f, v238
	v_lshlrev_b32_e32 v238, 2, v238
	v_and_b32_e32 v239, 0x80000000, v239
	v_or_b32_e32 v96, v239, v238
	v_sub_u32_e32 v238, v236, v97
	v_sub_u32_e32 v239, v237, v238
	v_or_b32_e32 v239, v239, v238
	v_and_b32_e32 v238, 0x7f, v238
	v_lshlrev_b32_e32 v238, 2, v238
	v_and_b32_e32 v239, 0x80000000, v239
	v_or_b32_e32 v97, v239, v238
	v_sub_u32_e32 v238, v236, v99
	v_sub_u32_e32 v239, v237, v238
	v_or_b32_e32 v239, v239, v238
	v_and_b32_e32 v238, 0x7f, v238
	v_lshlrev_b32_e32 v238, 2, v238
	v_and_b32_e32 v239, 0x80000000, v239
	v_or_b32_e32 v99, v239, v238
	v_sub_u32_e32 v238, v236, v100
	v_sub_u32_e32 v239, v237, v238
	v_or_b32_e32 v239, v239, v238
	v_and_b32_e32 v238, 0x7f, v238
	v_lshlrev_b32_e32 v238, 2, v238
	v_and_b32_e32 v239, 0x80000000, v239
	v_or_b32_e32 v100, v239, v238
	v_sub_u32_e32 v238, v236, v101
	v_sub_u32_e32 v239, v237, v238
	v_or_b32_e32 v239, v239, v238
	v_and_b32_e32 v238, 0x7f, v238
	v_lshlrev_b32_e32 v238, 2, v238
	v_and_b32_e32 v239, 0x80000000, v239
	v_or_b32_e32 v101, v239, v238
	v_sub_u32_e32 v238, v236, v102
	v_sub_u32_e32 v239, v237, v238
	v_or_b32_e32 v239, v239, v238
	v_and_b32_e32 v238, 0x7f, v238
	v_lshlrev_b32_e32 v238, 2, v238
	v_and_b32_e32 v239, 0x80000000, v239
	v_or_b32_e32 v102, v239, v238
	v_sub_u32_e32 v238, v236, v104
	v_sub_u32_e32 v239, v237, v238
	v_or_b32_e32 v239, v239, v238
	v_and_b32_e32 v238, 0x7f, v238
	v_lshlrev_b32_e32 v238, 2, v238
	v_and_b32_e32 v239, 0x80000000, v239
	v_or_b32_e32 v104, v239, v238
	v_sub_u32_e32 v238, v236, v105
	v_sub_u32_e32 v239, v237, v238
	v_or_b32_e32 v239, v239, v238
	v_and_b32_e32 v238, 0x7f, v238
	v_lshlrev_b32_e32 v238, 2, v238
	v_and_b32_e32 v239, 0x80000000, v239
	v_or_b32_e32 v105, v239, v238
	v_sub_u32_e32 v238, v236, v106
	v_sub_u32_e32 v239, v237, v238
	v_or_b32_e32 v239, v239, v238
	v_and_b32_e32 v238, 0x7f, v238
	v_lshlrev_b32_e32 v238, 2, v238
	v_and_b32_e32 v239, 0x80000000, v239
	v_or_b32_e32 v106, v239, v238
	v_sub_u32_e32 v238, v236, v107
	v_sub_u32_e32 v239, v237, v238
	v_or_b32_e32 v239, v239, v238
	v_and_b32_e32 v238, 0x7f, v238
	v_lshlrev_b32_e32 v238, 2, v238
	v_and_b32_e32 v239, 0x80000000, v239
	v_or_b32_e32 v107, v239, v238
	v_sub_u32_e32 v238, v236, v109
	v_sub_u32_e32 v239, v237, v238
	v_or_b32_e32 v239, v239, v238
	v_and_b32_e32 v238, 0x7f, v238
	v_lshlrev_b32_e32 v238, 2, v238
	v_and_b32_e32 v239, 0x80000000, v239
	v_or_b32_e32 v109, v239, v238
	v_sub_u32_e32 v238, v236, v110
	v_sub_u32_e32 v239, v237, v238
	v_or_b32_e32 v239, v239, v238
	v_and_b32_e32 v238, 0x7f, v238
	v_lshlrev_b32_e32 v238, 2, v238
	v_and_b32_e32 v239, 0x80000000, v239
	v_or_b32_e32 v110, v239, v238
	v_sub_u32_e32 v238, v236, v111
	v_sub_u32_e32 v239, v237, v238
	v_or_b32_e32 v239, v239, v238
	v_and_b32_e32 v238, 0x7f, v238
	v_lshlrev_b32_e32 v238, 2, v238
	v_and_b32_e32 v239, 0x80000000, v239
	v_or_b32_e32 v111, v239, v238
	v_sub_u32_e32 v238, v236, v112
	v_sub_u32_e32 v239, v237, v238
	v_or_b32_e32 v239, v239, v238
	v_and_b32_e32 v238, 0x7f, v238
	v_lshlrev_b32_e32 v238, 2, v238
	v_and_b32_e32 v239, 0x80000000, v239
	v_or_b32_e32 v112, v239, v238
	v_sub_u32_e32 v238, v236, v114
	v_sub_u32_e32 v239, v237, v238
	v_or_b32_e32 v239, v239, v238
	v_and_b32_e32 v238, 0x7f, v238
	v_lshlrev_b32_e32 v238, 2, v238
	v_and_b32_e32 v239, 0x80000000, v239
	v_or_b32_e32 v114, v239, v238
	v_sub_u32_e32 v238, v236, v115
	v_sub_u32_e32 v239, v237, v238
	v_or_b32_e32 v239, v239, v238
	v_and_b32_e32 v238, 0x7f, v238
	v_lshlrev_b32_e32 v238, 2, v238
	v_and_b32_e32 v239, 0x80000000, v239
	v_or_b32_e32 v115, v239, v238
	v_sub_u32_e32 v238, v236, v116
	v_sub_u32_e32 v239, v237, v238
	v_or_b32_e32 v239, v239, v238
	v_and_b32_e32 v238, 0x7f, v238
	v_lshlrev_b32_e32 v238, 2, v238
	v_and_b32_e32 v239, 0x80000000, v239
	v_or_b32_e32 v116, v239, v238
	v_sub_u32_e32 v238, v236, v117
	v_sub_u32_e32 v239, v237, v238
	v_or_b32_e32 v239, v239, v238
	v_and_b32_e32 v238, 0x7f, v238
	v_lshlrev_b32_e32 v238, 2, v238
	v_and_b32_e32 v239, 0x80000000, v239
	v_or_b32_e32 v117, v239, v238
	v_sub_u32_e32 v238, v236, v119
	v_sub_u32_e32 v239, v237, v238
	v_or_b32_e32 v239, v239, v238
	v_and_b32_e32 v238, 0x7f, v238
	v_lshlrev_b32_e32 v238, 2, v238
	v_and_b32_e32 v239, 0x80000000, v239
	v_or_b32_e32 v119, v239, v238
	v_sub_u32_e32 v238, v236, v120
	v_sub_u32_e32 v239, v237, v238
	v_or_b32_e32 v239, v239, v238
	v_and_b32_e32 v238, 0x7f, v238
	v_lshlrev_b32_e32 v238, 2, v238
	v_and_b32_e32 v239, 0x80000000, v239
	v_or_b32_e32 v120, v239, v238
	v_sub_u32_e32 v238, v236, v121
	v_sub_u32_e32 v239, v237, v238
	v_or_b32_e32 v239, v239, v238
	v_and_b32_e32 v238, 0x7f, v238
	v_lshlrev_b32_e32 v238, 2, v238
	v_and_b32_e32 v239, 0x80000000, v239
	v_or_b32_e32 v121, v239, v238
	v_sub_u32_e32 v238, v236, v122
	v_sub_u32_e32 v239, v237, v238
	v_or_b32_e32 v239, v239, v238
	v_and_b32_e32 v238, 0x7f, v238
	v_lshlrev_b32_e32 v238, 2, v238
	v_and_b32_e32 v239, 0x80000000, v239
	v_or_b32_e32 v122, v239, v238
	v_sub_u32_e32 v238, v236, v124
	v_sub_u32_e32 v239, v237, v238
	v_or_b32_e32 v239, v239, v238
	v_and_b32_e32 v238, 0x7f, v238
	v_lshlrev_b32_e32 v238, 2, v238
	v_and_b32_e32 v239, 0x80000000, v239
	v_or_b32_e32 v124, v239, v238
	v_sub_u32_e32 v238, v236, v125
	v_sub_u32_e32 v239, v237, v238
	v_or_b32_e32 v239, v239, v238
	v_and_b32_e32 v238, 0x7f, v238
	v_lshlrev_b32_e32 v238, 2, v238
	v_and_b32_e32 v239, 0x80000000, v239
	v_or_b32_e32 v125, v239, v238
	v_sub_u32_e32 v238, v236, v126
	v_sub_u32_e32 v239, v237, v238
	v_or_b32_e32 v239, v239, v238
	v_and_b32_e32 v238, 0x7f, v238
	v_lshlrev_b32_e32 v238, 2, v238
	v_and_b32_e32 v239, 0x80000000, v239
	v_or_b32_e32 v126, v239, v238
	v_sub_u32_e32 v238, v236, v127
	v_sub_u32_e32 v239, v237, v238
	v_or_b32_e32 v239, v239, v238
	v_and_b32_e32 v238, 0x7f, v238
	v_lshlrev_b32_e32 v238, 2, v238
	v_and_b32_e32 v239, 0x80000000, v239
	v_or_b32_e32 v127, v239, v238
.LBB0_124:
	s_waitcnt vmcnt(1)
	v_mov_b64_e32 v[16:17], v[4:5]
	v_mov_b32_e32 v36, v22
	v_mov_b64_e32 v[14:15], v[2:3]
	global_load_dwordx4 v[2:5], v[32:33], off offset:-64
	global_load_dwordx4 v[6:9], v[32:33], off
	s_load_dwordx2 s[48:49], s[80:81], 0xd0
	v_cndmask_b32_e64 v41, v195, v36, s[38:39]
	v_add_u32_e32 v46, 0x80, v36
	v_lshl_add_u64 v[32:33], v[32:33], 0, s[94:95]
	s_waitcnt lgkmcnt(0)
	s_add_u32 s2, s48, s46
	s_addc_u32 s3, s49, s47
	global_load_dword v40, v1, s[2:3]
	s_add_i32 s2, s28, 0
	s_add_i32 s2, s2, 0x11400
	s_addk_i32 s28, 0x200
	s_add_u32 s46, s46, 4
	s_addc_u32 s47, s47, 0
	s_cmpk_eq_i32 s28, 0xe00
	ds_read_b128 v[214:217], v78
	ds_read_b128 v[218:221], v78 offset:64
	v_bfi_b32 v206, v205, v79, s2
	ds_read_b32 v206, v206
	v_bfi_b32 v207, v205, v80, s2
	ds_read_b32 v207, v207
	v_bfi_b32 v208, v205, v81, s2
	ds_read_b32 v208, v208
	v_bfi_b32 v209, v205, v82, s2
	ds_read_b32 v209, v209
	ds_read_b128 v[222:225], v83
	ds_read_b128 v[226:229], v83 offset:64
	s_waitcnt vmcnt(3) lgkmcnt(6)
	v_mfma_f32_16x16x32_bf16 v[230:233], v[214:217], v[14:17], 0
	v_mfma_f32_16x16x32_bf16 v[230:233], v[218:221], v[10:13], v[230:233]
	v_ashrrev_i32_e32 v210, 31, v79
	v_and_b32_e32 v210, 0xff800000, v210
	v_ashrrev_i32_e32 v211, 31, v80
	v_and_b32_e32 v211, 0xff800000, v211
	v_ashrrev_i32_e32 v212, 31, v81
	v_and_b32_e32 v212, 0xff800000, v212
	v_ashrrev_i32_e32 v213, 31, v82
	v_and_b32_e32 v213, 0xff800000, v213
	s_nop 1
	s_waitcnt lgkmcnt(2)
	v_add_f32_e32 v234, v230, v206
	v_add_f32_e32 v47, v234, v210
	v_add_f32_e32 v234, v231, v207
	v_add_f32_e32 v48, v234, v211
	v_add_f32_e32 v234, v232, v208
	v_add_f32_e32 v49, v234, v212
	v_add_f32_e32 v234, v233, v209
	v_add_f32_e32 v50, v234, v213
	v_max3_f32 v36, v47, s96, v48
	v_max3_f32 v51, v36, v49, v50
	v_bfi_b32 v206, v205, v84, s2
	ds_read_b32 v206, v206
	v_bfi_b32 v207, v205, v85, s2
	ds_read_b32 v207, v207
	v_bfi_b32 v208, v205, v86, s2
	ds_read_b32 v208, v208
	v_bfi_b32 v209, v205, v87, s2
	ds_read_b32 v209, v209
	ds_read_b128 v[214:217], v88
	ds_read_b128 v[218:221], v88 offset:64
	s_waitcnt lgkmcnt(6)
	v_mfma_f32_16x16x32_bf16 v[230:233], v[222:225], v[14:17], 0
	v_mfma_f32_16x16x32_bf16 v[230:233], v[226:229], v[10:13], v[230:233]
	v_ashrrev_i32_e32 v210, 31, v84
	v_and_b32_e32 v210, 0xff800000, v210
	v_ashrrev_i32_e32 v211, 31, v85
	v_and_b32_e32 v211, 0xff800000, v211
	v_ashrrev_i32_e32 v212, 31, v86
	v_and_b32_e32 v212, 0xff800000, v212
	v_ashrrev_i32_e32 v213, 31, v87
	v_and_b32_e32 v213, 0xff800000, v213
	s_nop 1
	s_waitcnt lgkmcnt(2)
	v_add_f32_e32 v234, v230, v206
	v_add_f32_e32 v52, v234, v210
	v_add_f32_e32 v234, v231, v207
	v_add_f32_e32 v53, v234, v211
	v_add_f32_e32 v234, v232, v208
	v_add_f32_e32 v51, v234, v212
	v_add_f32_e32 v234, v233, v209
	v_add_f32_e32 v54, v234, v213
	v_max3_f32 v36, v51, v52, v53
	v_max3_f32 v55, v36, v51, v54
	v_bfi_b32 v206, v205, v89, s2
	ds_read_b32 v206, v206
	v_bfi_b32 v207, v205, v90, s2
	ds_read_b32 v207, v207
	v_bfi_b32 v208, v205, v91, s2
	ds_read_b32 v208, v208
	v_bfi_b32 v209, v205, v92, s2
	ds_read_b32 v209, v209
	ds_read_b128 v[222:225], v93
	ds_read_b128 v[226:229], v93 offset:64
	s_waitcnt lgkmcnt(6)
	v_mfma_f32_16x16x32_bf16 v[230:233], v[214:217], v[14:17], 0
	v_mfma_f32_16x16x32_bf16 v[230:233], v[218:221], v[10:13], v[230:233]
	v_ashrrev_i32_e32 v210, 31, v89
	v_and_b32_e32 v210, 0xff800000, v210
	v_ashrrev_i32_e32 v211, 31, v90
	v_and_b32_e32 v211, 0xff800000, v211
	v_ashrrev_i32_e32 v212, 31, v91
	v_and_b32_e32 v212, 0xff800000, v212
	v_ashrrev_i32_e32 v213, 31, v92
	v_and_b32_e32 v213, 0xff800000, v213
	s_nop 1
	s_waitcnt lgkmcnt(2)
	v_add_f32_e32 v234, v230, v206
	v_add_f32_e32 v56, v234, v210
	v_add_f32_e32 v234, v231, v207
	v_add_f32_e32 v57, v234, v211
	v_add_f32_e32 v234, v232, v208
	v_add_f32_e32 v55, v234, v212
	v_add_f32_e32 v234, v233, v209
	v_add_f32_e32 v61, v234, v213
	v_max3_f32 v36, v55, v56, v57
	v_max3_f32 v58, v36, v55, v61
	v_bfi_b32 v206, v205, v94, s2
	ds_read_b32 v206, v206
	v_bfi_b32 v207, v205, v95, s2
	ds_read_b32 v207, v207
	v_bfi_b32 v208, v205, v96, s2
	ds_read_b32 v208, v208
	v_bfi_b32 v209, v205, v97, s2
	ds_read_b32 v209, v209
	ds_read_b128 v[214:217], v98
	ds_read_b128 v[218:221], v98 offset:64
	s_waitcnt lgkmcnt(6)
	v_mfma_f32_16x16x32_bf16 v[230:233], v[222:225], v[14:17], 0
	v_mfma_f32_16x16x32_bf16 v[230:233], v[226:229], v[10:13], v[230:233]
	v_ashrrev_i32_e32 v210, 31, v94
	v_and_b32_e32 v210, 0xff800000, v210
	v_ashrrev_i32_e32 v211, 31, v95
	v_and_b32_e32 v211, 0xff800000, v211
	v_ashrrev_i32_e32 v212, 31, v96
	v_and_b32_e32 v212, 0xff800000, v212
	v_ashrrev_i32_e32 v213, 31, v97
	v_and_b32_e32 v213, 0xff800000, v213
	s_nop 1
	s_waitcnt lgkmcnt(2)
	v_add_f32_e32 v234, v230, v206
	v_add_f32_e32 v62, v234, v210
	v_add_f32_e32 v234, v231, v207
	v_add_f32_e32 v63, v234, v211
	v_add_f32_e32 v234, v232, v208
	v_add_f32_e32 v64, v234, v212
	v_add_f32_e32 v234, v233, v209
	v_add_f32_e32 v65, v234, v213
	v_max3_f32 v36, v58, v62, v63
	v_max3_f32 v58, v36, v64, v65
	v_bfi_b32 v206, v205, v99, s2
	ds_read_b32 v206, v206
	v_bfi_b32 v207, v205, v100, s2
	ds_read_b32 v207, v207
	v_bfi_b32 v208, v205, v101, s2
	ds_read_b32 v208, v208
	v_bfi_b32 v209, v205, v102, s2
	ds_read_b32 v209, v209
	ds_read_b128 v[222:225], v103
	ds_read_b128 v[226:229], v103 offset:64
	s_waitcnt lgkmcnt(6)
	v_mfma_f32_16x16x32_bf16 v[230:233], v[214:217], v[14:17], 0
	v_mfma_f32_16x16x32_bf16 v[230:233], v[218:221], v[10:13], v[230:233]
	v_ashrrev_i32_e32 v210, 31, v99
	v_and_b32_e32 v210, 0xff800000, v210
	v_ashrrev_i32_e32 v211, 31, v100
	v_and_b32_e32 v211, 0xff800000, v211
	v_ashrrev_i32_e32 v212, 31, v101
	v_and_b32_e32 v212, 0xff800000, v212
	v_ashrrev_i32_e32 v213, 31, v102
	v_and_b32_e32 v213, 0xff800000, v213
	s_nop 1
	s_waitcnt lgkmcnt(2)
	v_add_f32_e32 v234, v230, v206
	v_add_f32_e32 v137, v234, v210
	v_add_f32_e32 v234, v231, v207
	v_add_f32_e32 v142, v234, v211
	v_add_f32_e32 v234, v232, v208
	v_add_f32_e32 v143, v234, v212
	v_add_f32_e32 v234, v233, v209
	v_add_f32_e32 v144, v234, v213
	v_max3_f32 v36, v58, v137, v142
	v_max3_f32 v58, v36, v143, v144
	v_bfi_b32 v206, v205, v104, s2
	ds_read_b32 v206, v206
	v_bfi_b32 v207, v205, v105, s2
	ds_read_b32 v207, v207
	v_bfi_b32 v208, v205, v106, s2
	ds_read_b32 v208, v208
	v_bfi_b32 v209, v205, v107, s2
	ds_read_b32 v209, v209
	ds_read_b128 v[214:217], v108
	ds_read_b128 v[218:221], v108 offset:64
	s_waitcnt lgkmcnt(6)
	v_mfma_f32_16x16x32_bf16 v[230:233], v[222:225], v[14:17], 0
	v_mfma_f32_16x16x32_bf16 v[230:233], v[226:229], v[10:13], v[230:233]
	v_ashrrev_i32_e32 v210, 31, v104
	v_and_b32_e32 v210, 0xff800000, v210
	v_ashrrev_i32_e32 v211, 31, v105
	v_and_b32_e32 v211, 0xff800000, v211
	v_ashrrev_i32_e32 v212, 31, v106
	v_and_b32_e32 v212, 0xff800000, v212
	v_ashrrev_i32_e32 v213, 31, v107
	v_and_b32_e32 v213, 0xff800000, v213
	s_nop 1
	s_waitcnt lgkmcnt(2)
	v_add_f32_e32 v234, v230, v206
	v_add_f32_e32 v145, v234, v210
	v_add_f32_e32 v234, v231, v207
	v_add_f32_e32 v162, v234, v211
	v_add_f32_e32 v234, v232, v208
	v_add_f32_e32 v163, v234, v212
	v_add_f32_e32 v234, v233, v209
	v_add_f32_e32 v164, v234, v213
	v_max3_f32 v36, v58, v145, v162
	v_max3_f32 v58, v36, v163, v164
	v_bfi_b32 v206, v205, v109, s2
	ds_read_b32 v206, v206
	v_bfi_b32 v207, v205, v110, s2
	ds_read_b32 v207, v207
	v_bfi_b32 v208, v205, v111, s2
	ds_read_b32 v208, v208
	v_bfi_b32 v209, v205, v112, s2
	ds_read_b32 v209, v209
	ds_read_b128 v[222:225], v113
	ds_read_b128 v[226:229], v113 offset:64
	s_waitcnt lgkmcnt(6)
	v_mfma_f32_16x16x32_bf16 v[230:233], v[214:217], v[14:17], 0
	v_mfma_f32_16x16x32_bf16 v[230:233], v[218:221], v[10:13], v[230:233]
	v_ashrrev_i32_e32 v210, 31, v109
	v_and_b32_e32 v210, 0xff800000, v210
	v_ashrrev_i32_e32 v211, 31, v110
	v_and_b32_e32 v211, 0xff800000, v211
	v_ashrrev_i32_e32 v212, 31, v111
	v_and_b32_e32 v212, 0xff800000, v212
	v_ashrrev_i32_e32 v213, 31, v112
	v_and_b32_e32 v213, 0xff800000, v213
	s_nop 1
	s_waitcnt lgkmcnt(2)
	v_add_f32_e32 v234, v230, v206
	v_add_f32_e32 v165, v234, v210
	v_add_f32_e32 v234, v231, v207
	v_add_f32_e32 v166, v234, v211
	v_add_f32_e32 v234, v232, v208
	v_add_f32_e32 v167, v234, v212
	v_add_f32_e32 v234, v233, v209
	v_add_f32_e32 v168, v234, v213
	v_max3_f32 v36, v58, v165, v166
	v_max3_f32 v58, v36, v167, v168
	v_bfi_b32 v206, v205, v114, s2
	ds_read_b32 v206, v206
	v_bfi_b32 v207, v205, v115, s2
	ds_read_b32 v207, v207
	v_bfi_b32 v208, v205, v116, s2
	ds_read_b32 v208, v208
	v_bfi_b32 v209, v205, v117, s2
	ds_read_b32 v209, v209
	ds_read_b128 v[214:217], v118
	ds_read_b128 v[218:221], v118 offset:64
	s_waitcnt lgkmcnt(6)
	v_mfma_f32_16x16x32_bf16 v[230:233], v[222:225], v[14:17], 0
	v_mfma_f32_16x16x32_bf16 v[230:233], v[226:229], v[10:13], v[230:233]
	v_ashrrev_i32_e32 v210, 31, v114
	v_and_b32_e32 v210, 0xff800000, v210
	v_ashrrev_i32_e32 v211, 31, v115
	v_and_b32_e32 v211, 0xff800000, v211
	v_ashrrev_i32_e32 v212, 31, v116
	v_and_b32_e32 v212, 0xff800000, v212
	v_ashrrev_i32_e32 v213, 31, v117
	v_and_b32_e32 v213, 0xff800000, v213
	s_nop 1
	s_waitcnt lgkmcnt(2)
	v_add_f32_e32 v234, v230, v206
	v_add_f32_e32 v169, v234, v210
	v_add_f32_e32 v234, v231, v207
	v_add_f32_e32 v170, v234, v211
	v_add_f32_e32 v234, v232, v208
	v_add_f32_e32 v171, v234, v212
	v_add_f32_e32 v234, v233, v209
	v_add_f32_e32 v172, v234, v213
	v_max3_f32 v36, v58, v169, v170
	v_max3_f32 v58, v36, v171, v172
	v_bfi_b32 v206, v205, v119, s2
	ds_read_b32 v206, v206
	v_bfi_b32 v207, v205, v120, s2
	ds_read_b32 v207, v207
	v_bfi_b32 v208, v205, v121, s2
	ds_read_b32 v208, v208
	v_bfi_b32 v209, v205, v122, s2
	ds_read_b32 v209, v209
	ds_read_b128 v[222:225], v123
	ds_read_b128 v[226:229], v123 offset:64
	s_waitcnt lgkmcnt(6)
	v_mfma_f32_16x16x32_bf16 v[230:233], v[214:217], v[14:17], 0
	v_mfma_f32_16x16x32_bf16 v[230:233], v[218:221], v[10:13], v[230:233]
	v_ashrrev_i32_e32 v210, 31, v119
	v_and_b32_e32 v210, 0xff800000, v210
	v_ashrrev_i32_e32 v211, 31, v120
	v_and_b32_e32 v211, 0xff800000, v211
	v_ashrrev_i32_e32 v212, 31, v121
	v_and_b32_e32 v212, 0xff800000, v212
	v_ashrrev_i32_e32 v213, 31, v122
	v_and_b32_e32 v213, 0xff800000, v213
	s_nop 1
	s_waitcnt lgkmcnt(2)
	v_add_f32_e32 v234, v230, v206
	v_add_f32_e32 v173, v234, v210
	v_add_f32_e32 v234, v231, v207
	v_add_f32_e32 v174, v234, v211
	v_add_f32_e32 v234, v232, v208
	v_add_f32_e32 v175, v234, v212
	v_add_f32_e32 v234, v233, v209
	v_add_f32_e32 v176, v234, v213
	v_max3_f32 v36, v58, v173, v174
	v_max3_f32 v58, v36, v175, v176
	v_bfi_b32 v206, v205, v124, s2
	ds_read_b32 v206, v206
	v_bfi_b32 v207, v205, v125, s2
	ds_read_b32 v207, v207
	v_bfi_b32 v208, v205, v126, s2
	ds_read_b32 v208, v208
	v_bfi_b32 v209, v205, v127, s2
	ds_read_b32 v209, v209
	s_waitcnt lgkmcnt(4)
	v_mfma_f32_16x16x32_bf16 v[230:233], v[222:225], v[14:17], 0
	v_mfma_f32_16x16x32_bf16 v[230:233], v[226:229], v[10:13], v[230:233]
	v_ashrrev_i32_e32 v210, 31, v124
	v_and_b32_e32 v210, 0xff800000, v210
	v_ashrrev_i32_e32 v211, 31, v125
	v_and_b32_e32 v211, 0xff800000, v211
	v_ashrrev_i32_e32 v212, 31, v126
	v_and_b32_e32 v212, 0xff800000, v212
	v_ashrrev_i32_e32 v213, 31, v127
	v_and_b32_e32 v213, 0xff800000, v213
	s_nop 1
	s_waitcnt lgkmcnt(0)
	v_add_f32_e32 v234, v230, v206
	v_add_f32_e32 v36, v234, v210
	v_add_f32_e32 v234, v231, v207
	v_add_f32_e32 v37, v234, v211
	v_add_f32_e32 v234, v232, v208
	v_add_f32_e32 v38, v234, v212
	v_add_f32_e32 v234, v233, v209
	v_add_f32_e32 v39, v234, v213
	v_max3_f32 v10, v58, v36, v37
	v_max3_f32 v10, v10, v38, v39
	ds_swizzle_b32 v11, v10 offset:swizzle(SWAP,16)
	s_waitcnt lgkmcnt(0)
	v_max_f32_e32 v11, v11, v11
	v_max_f32_e32 v10, v10, v11
	ds_bpermute_b32 v11, v19, v10
	s_waitcnt vmcnt(0) lgkmcnt(0)
	v_max3_f32 v41, v10, v11, v40
	v_sub_f32_e32 v15, v52, v41
	v_mul_f32_e32 v15, 0x3fb8aa3b, v15
	v_exp_f32_e32 v138, v15
	v_sub_f32_e32 v15, v53, v41
	v_mul_f32_e32 v15, 0x3fb8aa3b, v15
	v_exp_f32_e32 v139, v15
	v_sub_f32_e32 v15, v51, v41
	v_mul_f32_e32 v15, 0x3fb8aa3b, v15
	v_exp_f32_e32 v140, v15
	v_sub_f32_e32 v15, v54, v41
	v_mul_f32_e32 v15, 0x3fb8aa3b, v15
	v_exp_f32_e32 v141, v15
	v_sub_f32_e32 v15, v56, v41
	v_mul_f32_e32 v15, 0x3fb8aa3b, v15
	v_exp_f32_e32 v58, v15
	v_sub_f32_e32 v15, v57, v41
	v_mul_f32_e32 v15, 0x3fb8aa3b, v15
	v_exp_f32_e32 v59, v15
	v_sub_f32_e32 v15, v55, v41
	v_sub_f32_e32 v10, v47, v41
	v_mul_f32_e32 v15, 0x3fb8aa3b, v15
	v_mul_f32_e32 v10, 0x3fb8aa3b, v10
	v_sub_f32_e32 v11, v48, v41
	v_exp_f32_e32 v60, v15
	v_sub_f32_e32 v15, v61, v41
	v_exp_f32_e32 v10, v10
	v_mul_f32_e32 v11, 0x3fb8aa3b, v11
	v_mul_f32_e32 v15, 0x3fb8aa3b, v15
	v_exp_f32_e32 v11, v11
	v_exp_f32_e32 v61, v15
	v_sub_f32_e32 v15, v62, v41
	v_mul_f32_e32 v15, 0x3fb8aa3b, v15
	v_exp_f32_e32 v62, v15
	v_sub_f32_e32 v15, v63, v41
	v_add_f32_e32 v12, 0, v10
	v_mul_f32_e32 v15, 0x3fb8aa3b, v15
	v_add_f32_e32 v13, v11, v12
	v_sub_f32_e32 v12, v49, v41
	v_exp_f32_e32 v63, v15
	v_sub_f32_e32 v15, v64, v41
	v_mul_f32_e32 v12, 0x3fb8aa3b, v12
	v_mul_f32_e32 v15, 0x3fb8aa3b, v15
	v_exp_f32_e32 v12, v12
	v_exp_f32_e32 v64, v15
	v_sub_f32_e32 v15, v65, v41
	v_mul_f32_e32 v15, 0x3fb8aa3b, v15
	v_exp_f32_e32 v65, v15
	v_sub_f32_e32 v15, v137, v41
	v_mul_f32_e32 v15, 0x3fb8aa3b, v15
	v_add_f32_e32 v14, v12, v13
	v_sub_f32_e32 v13, v50, v41
	v_exp_f32_e32 v50, v15
	v_sub_f32_e32 v15, v142, v41
	v_mul_f32_e32 v13, 0x3fb8aa3b, v13
	v_mul_f32_e32 v15, 0x3fb8aa3b, v15
	v_exp_f32_e32 v13, v13
	v_exp_f32_e32 v51, v15
	v_sub_f32_e32 v15, v143, v41
	v_mul_f32_e32 v15, 0x3fb8aa3b, v15
	v_exp_f32_e32 v52, v15
	v_sub_f32_e32 v15, v144, v41
	v_mul_f32_e32 v15, 0x3fb8aa3b, v15
	v_add_f32_e32 v14, v13, v14
	v_exp_f32_e32 v53, v15
	v_sub_f32_e32 v15, v145, v41
	v_add_f32_e32 v14, v138, v14
	v_mul_f32_e32 v15, 0x3fb8aa3b, v15
	v_add_f32_e32 v14, v139, v14
	v_exp_f32_e32 v54, v15
	v_sub_f32_e32 v15, v162, v41
	v_add_f32_e32 v14, v140, v14
	v_mul_f32_e32 v15, 0x3fb8aa3b, v15
	v_add_f32_e32 v14, v141, v14
	v_exp_f32_e32 v55, v15
	v_sub_f32_e32 v15, v163, v41
	v_add_f32_e32 v14, v58, v14
	v_mul_f32_e32 v15, 0x3fb8aa3b, v15
	v_add_f32_e32 v14, v59, v14
	v_exp_f32_e32 v56, v15
	v_sub_f32_e32 v15, v164, v41
	v_add_f32_e32 v14, v60, v14
	v_mul_f32_e32 v15, 0x3fb8aa3b, v15
	v_add_f32_e32 v14, v61, v14
	v_exp_f32_e32 v57, v15
	v_sub_f32_e32 v15, v165, v41
	v_add_f32_e32 v14, v62, v14
	v_mul_f32_e32 v15, 0x3fb8aa3b, v15
	v_add_f32_e32 v14, v63, v14
	v_exp_f32_e32 v42, v15
	v_sub_f32_e32 v15, v166, v41
	v_add_f32_e32 v14, v64, v14
	v_mul_f32_e32 v15, 0x3fb8aa3b, v15
	v_add_f32_e32 v14, v65, v14
	v_exp_f32_e32 v43, v15
	v_sub_f32_e32 v15, v167, v41
	v_add_f32_e32 v14, v50, v14
	v_mul_f32_e32 v15, 0x3fb8aa3b, v15
	v_add_f32_e32 v14, v51, v14
	v_exp_f32_e32 v44, v15
	v_sub_f32_e32 v15, v168, v41
	v_add_f32_e32 v14, v52, v14
	v_mul_f32_e32 v15, 0x3fb8aa3b, v15
	v_add_f32_e32 v14, v53, v14
	v_exp_f32_e32 v45, v15
	v_sub_f32_e32 v15, v169, v41
	v_add_f32_e32 v14, v54, v14
	v_mul_f32_e32 v15, 0x3fb8aa3b, v15
	v_add_f32_e32 v14, v55, v14
	v_exp_f32_e32 v46, v15
	v_sub_f32_e32 v15, v170, v41
	v_add_f32_e32 v14, v56, v14
	v_mul_f32_e32 v15, 0x3fb8aa3b, v15
	v_add_f32_e32 v14, v57, v14
	v_exp_f32_e32 v47, v15
	v_sub_f32_e32 v15, v171, v41
	v_add_f32_e32 v14, v42, v14
	v_mul_f32_e32 v15, 0x3fb8aa3b, v15
	v_add_f32_e32 v14, v43, v14
	v_exp_f32_e32 v48, v15
	v_sub_f32_e32 v15, v172, v41
	v_add_f32_e32 v14, v44, v14
	v_mul_f32_e32 v15, 0x3fb8aa3b, v15
	v_add_f32_e32 v14, v45, v14
	v_exp_f32_e32 v49, v15
	v_add_f32_e32 v14, v46, v14
	v_add_f32_e32 v14, v47, v14
	v_add_f32_e32 v14, v48, v14
	v_add_f32_e32 v15, v49, v14
	v_sub_f32_e32 v14, v173, v41
	v_mul_f32_e32 v14, 0x3fb8aa3b, v14
	v_exp_f32_e32 v14, v14
	v_sub_f32_e32 v36, v36, v41
	v_mul_f32_e32 v36, 0x3fb8aa3b, v36
	v_sub_f32_e32 v37, v37, v41
	v_add_f32_e32 v16, v14, v15
	v_sub_f32_e32 v15, v174, v41
	v_mul_f32_e32 v15, 0x3fb8aa3b, v15
	v_exp_f32_e32 v15, v15
	v_exp_f32_e32 v36, v36
	v_mul_f32_e32 v37, 0x3fb8aa3b, v37
	v_sub_f32_e32 v38, v38, v41
	v_add_f32_e32 v17, v15, v16
	v_sub_f32_e32 v16, v175, v41
	v_mul_f32_e32 v16, 0x3fb8aa3b, v16
	v_exp_f32_e32 v16, v16
	v_exp_f32_e32 v37, v37
	v_mul_f32_e32 v38, 0x3fb8aa3b, v38
	v_sub_f32_e32 v39, v39, v41
	v_add_f32_e32 v137, v16, v17
	v_sub_f32_e32 v17, v176, v41
	v_mul_f32_e32 v17, 0x3fb8aa3b, v17
	v_exp_f32_e32 v17, v17
	v_exp_f32_e32 v38, v38
	v_mul_f32_e32 v39, 0x3fb8aa3b, v39
	v_exp_f32_e32 v39, v39
	v_add_f32_e32 v137, v17, v137
	v_add_f32_e32 v137, v36, v137
	v_add_f32_e32 v137, v37, v137
	v_add_f32_e32 v137, v38, v137
	v_add_f32_e32 v137, v39, v137
	ds_swizzle_b32 v142, v137 offset:swizzle(SWAP,16)
	v_sub_f32_e32 v40, v40, v41
	v_mul_f32_e32 v40, 0x3fb8aa3b, v40
	v_exp_f32_e32 v40, v40
	s_waitcnt lgkmcnt(0)
	v_add_f32_e32 v137, v137, v142
	ds_bpermute_b32 v142, v19, v137
	s_waitcnt lgkmcnt(0)
	v_add_f32_e32 v137, v137, v142
	v_add_f32_e32 v40, v40, v137
	v_div_scale_f32 v41, s[2:3], v40, v40, 1.0
	v_rcp_f32_e32 v137, v41
	s_nop 0
	v_fma_f32 v142, -v41, v137, 1.0
	v_fmac_f32_e32 v137, v142, v137
	v_div_scale_f32 v142, vcc, 1.0, v40, 1.0
	v_mul_f32_e32 v143, v142, v137
	v_fma_f32 v144, -v41, v143, v142
	v_fmac_f32_e32 v143, v144, v137
	v_fma_f32 v41, -v41, v143, v142
	v_div_fmas_f32 v41, v41, v137, v143
	v_div_fixup_f32 v40, v41, v40, 1.0
	v_pk_mul_f32 v[12:13], v[12:13], v[40:41] op_sel_hi:[1,0]
	v_pk_mul_f32 v[10:11], v[10:11], v[40:41] op_sel_hi:[1,0]
	v_pk_mul_f32 v[140:141], v[140:141], v[40:41] op_sel_hi:[1,0]
	v_pk_mul_f32 v[138:139], v[138:139], v[40:41] op_sel_hi:[1,0]
	v_add_u32_e32 v137, 0x9000, v132
	v_cvt_pk_bf16_f32 v10, v10, v11
	v_cvt_pk_bf16_f32 v11, v12, v13
	v_cvt_pk_bf16_f32 v12, v138, v139
	v_cvt_pk_bf16_f32 v13, v140, v141
	ds_read2_b64 v[138:141], v137 offset1:4
	s_waitcnt lgkmcnt(0)
	v_mfma_f32_16x16x32_bf16 v[142:145], v[138:141], v[10:13], 0
	v_add_u32_e32 v138, 0xb000, v132
	v_add_u32_e32 v139, 0xd000, v132
	v_add_u32_e32 v140, 0xf000, v132
	ds_read2_b64 v[162:165], v138 offset0:32 offset1:36
	ds_read2_b64 v[166:169], v139 offset0:64 offset1:68
	ds_read2_b64 v[170:173], v140 offset0:96 offset1:100
	v_pk_mul_f32 v[58:59], v[58:59], v[40:41] op_sel_hi:[1,0]
	s_waitcnt lgkmcnt(2)
	v_mfma_f32_16x16x32_bf16 v[162:165], v[162:165], v[10:13], 0
	v_mul_f32_e64 v60, v60, v40
	v_mul_f32_e64 v61, v61, v40
	v_pk_mul_f32 v[52:53], v[52:53], v[40:41] op_sel_hi:[1,0]
	v_pk_mul_f32 v[50:51], v[50:51], v[40:41] op_sel_hi:[1,0]
	s_waitcnt lgkmcnt(1)
	v_mfma_f32_16x16x32_bf16 v[166:169], v[166:169], v[10:13], 0
	v_mul_f32_e64 v56, v56, v40
	v_mul_f32_e64 v57, v57, v40
	v_pk_mul_f32 v[54:55], v[54:55], v[40:41] op_sel_hi:[1,0]
	v_pk_mul_f32 v[44:45], v[44:45], v[40:41] op_sel_hi:[1,0]
	s_waitcnt lgkmcnt(0)
	v_mfma_f32_16x16x32_bf16 v[10:13], v[170:173], v[10:13], 0
	v_mul_f32_e64 v170, v64, v40
	v_mul_f32_e64 v171, v65, v40
	v_pk_mul_f32 v[64:65], v[62:63], v[40:41] op_sel_hi:[1,0]
	v_cvt_pk_bf16_f32 v62, v58, v59
	v_add_u32_e32 v58, 0x9000, v133
	v_cvt_pk_bf16_f32 v63, v60, v61
	v_cvt_pk_bf16_f32 v64, v64, v65
	v_cvt_pk_bf16_f32 v65, v170, v171
	ds_read2_b64 v[170:173], v58 offset1:4
	v_add_u32_e32 v59, 0xb000, v133
	s_waitcnt lgkmcnt(0)
	v_mfma_f32_16x16x32_bf16 v[142:145], v[170:173], v[62:65], v[142:145]
	ds_read2_b64 v[170:173], v59 offset0:32 offset1:36
	v_add_u32_e32 v60, 0xd000, v133
	v_add_u32_e32 v61, 0xf000, v133
	s_waitcnt lgkmcnt(0)
	v_mfma_f32_16x16x32_bf16 v[162:165], v[170:173], v[62:65], v[162:165]
	ds_read2_b64 v[170:173], v60 offset0:64 offset1:68
	v_pk_mul_f32 v[42:43], v[42:43], v[40:41] op_sel_hi:[1,0]
	v_pk_mul_f32 v[48:49], v[48:49], v[40:41] op_sel_hi:[1,0]
	s_waitcnt lgkmcnt(0)
	v_mfma_f32_16x16x32_bf16 v[166:169], v[170:173], v[62:65], v[166:169]
	ds_read2_b64 v[170:173], v61 offset0:96 offset1:100
	v_cvt_pk_bf16_f32 v50, v50, v51
	v_cvt_pk_bf16_f32 v51, v52, v53
	v_cvt_pk_bf16_f32 v52, v54, v55
	v_cvt_pk_bf16_f32 v53, v56, v57
	v_add_u32_e32 v56, 0x9000, v134
	s_waitcnt lgkmcnt(0)
	v_mfma_f32_16x16x32_bf16 v[10:13], v[170:173], v[62:65], v[10:13]
	ds_read2_b64 v[62:65], v56 offset1:4
	v_add_u32_e32 v57, 0xb000, v134
	v_pk_mul_f32 v[46:47], v[46:47], v[40:41] op_sel_hi:[1,0]
	s_waitcnt lgkmcnt(0)
	v_mfma_f32_16x16x32_bf16 v[142:145], v[62:65], v[50:53], v[142:145]
	ds_read2_b64 v[62:65], v57 offset0:32 offset1:36
	v_add_u32_e32 v141, 0xd000, v135
	v_pk_mul_f32 v[16:17], v[16:17], v[40:41] op_sel_hi:[1,0]
	s_waitcnt lgkmcnt(0)
	v_mfma_f32_16x16x32_bf16 v[162:165], v[62:65], v[50:53], v[162:165]
	v_add_u32_e32 v62, 0xd000, v134
	ds_read2_b64 v[170:173], v62 offset0:64 offset1:68
	v_add_u32_e32 v63, 0xf000, v134
	v_add_u32_e32 v64, 0x9000, v135
	s_waitcnt lgkmcnt(0)
	v_mfma_f32_16x16x32_bf16 v[166:169], v[170:173], v[50:53], v[166:169]
	ds_read2_b64 v[170:173], v63 offset0:96 offset1:100
	v_cvt_pk_bf16_f32 v42, v42, v43
	v_cvt_pk_bf16_f32 v43, v44, v45
	v_cvt_pk_bf16_f32 v44, v46, v47
	v_cvt_pk_bf16_f32 v45, v48, v49
	ds_read2_b64 v[46:49], v64 offset1:4
	v_add_u32_e32 v65, 0xb000, v135
	s_waitcnt lgkmcnt(1)
	v_mfma_f32_16x16x32_bf16 v[10:13], v[170:173], v[50:53], v[10:13]
	ds_read2_b64 v[50:53], v65 offset0:32 offset1:36
	v_pk_mul_f32 v[14:15], v[14:15], v[40:41] op_sel_hi:[1,0]
	v_pk_mul_f32 v[38:39], v[38:39], v[40:41] op_sel_hi:[1,0]
	s_waitcnt lgkmcnt(1)
	v_mfma_f32_16x16x32_bf16 v[46:49], v[46:49], v[42:45], v[142:145]
	v_mul_f32_e64 v36, v36, v40
	v_mul_f32_e64 v37, v37, v40
	s_nop 0
	ds_read2_b64 v[142:145], v141 offset0:64 offset1:68
	s_waitcnt lgkmcnt(1)
	v_mfma_f32_16x16x32_bf16 v[50:53], v[50:53], v[42:45], v[162:165]
	s_waitcnt lgkmcnt(0)
	v_mfma_f32_16x16x32_bf16 v[162:165], v[142:145], v[42:45], v[166:169]
	v_add_u32_e32 v142, 0xf000, v135
	v_add_u32_e32 v143, 0x9000, v136
	s_nop 0
	ds_read2_b64 v[166:169], v142 offset0:96 offset1:100
	v_cvt_pk_bf16_f32 v14, v14, v15
	v_cvt_pk_bf16_f32 v15, v16, v17
	v_cvt_pk_bf16_f32 v16, v36, v37
	v_cvt_pk_bf16_f32 v17, v38, v39
	ds_read2_b64 v[36:39], v143 offset1:4
	v_add_u32_e32 v145, 0xd000, v136
	s_waitcnt lgkmcnt(1)
	v_mfma_f32_16x16x32_bf16 v[10:13], v[166:169], v[42:45], v[10:13]
	v_add_u32_e32 v144, 0xb000, v136
	ds_read2_b64 v[40:43], v144 offset0:32 offset1:36
	s_waitcnt lgkmcnt(1)
	v_mfma_f32_16x16x32_bf16 v[36:39], v[36:39], v[14:17], v[46:49]
	s_nop 2
	ds_read2_b64 v[44:47], v145 offset0:64 offset1:68
	s_waitcnt lgkmcnt(0)
	v_mfma_f32_16x16x32_bf16 v[44:47], v[44:47], v[14:17], v[162:165]
	s_nop 2
	v_add_u32_e32 v162, 0xf000, v136
	v_mfma_f32_16x16x32_bf16 v[40:43], v[40:43], v[14:17], v[50:53]
	s_nop 2
	ds_read2_b64 v[48:51], v162 offset0:96 offset1:100
	s_waitcnt lgkmcnt(0)
	v_mfma_f32_16x16x32_bf16 v[10:13], v[48:51], v[14:17], v[10:13]
	v_cvt_pk_bf16_f32 v14, v36, v37
	v_cvt_pk_bf16_f32 v15, v38, v39
	global_store_dwordx2 v[34:35], v[14:15], off offset:-64
	v_cvt_pk_bf16_f32 v14, v40, v41
	v_cvt_pk_bf16_f32 v15, v42, v43
	global_store_dwordx2 v[34:35], v[14:15], off offset:-32
	v_cvt_pk_bf16_f32 v14, v44, v45
	v_cvt_pk_bf16_f32 v15, v46, v47
	global_store_dwordx2 v[34:35], v[14:15], off
	v_cvt_pk_bf16_f32 v10, v10, v11
	v_cvt_pk_bf16_f32 v11, v12, v13
	s_nop 4
	global_store_dwordx2 v[34:35], v[10:11], off offset:32
	v_mov_b64_e32 v[12:13], v[8:9]
	v_lshl_add_u64 v[34:35], v[34:35], 0, s[94:95]
	v_mov_b64_e32 v[10:11], v[6:7]
	s_cbranch_scc0 .LBB0_124
	v_add_u32_e32 v79, 0, v235
	v_add_u32_e32 v80, 1, v235
	v_add_u32_e32 v81, 2, v235
	v_add_u32_e32 v82, 3, v235
	v_add_u32_e32 v84, 16, v235
	v_add_u32_e32 v85, 17, v235
	v_add_u32_e32 v86, 18, v235
	v_add_u32_e32 v87, 19, v235
	v_add_u32_e32 v89, 32, v235
	v_add_u32_e32 v90, 33, v235
	v_add_u32_e32 v91, 34, v235
	v_add_u32_e32 v92, 35, v235
	v_add_u32_e32 v94, 48, v235
	v_add_u32_e32 v95, 49, v235
	v_add_u32_e32 v96, 50, v235
	v_add_u32_e32 v97, 51, v235
	v_add_u32_e32 v99, 64, v235
	v_add_u32_e32 v100, 65, v235
	v_add_u32_e32 v101, 66, v235
	v_add_u32_e32 v102, 67, v235
	v_add_u32_e32 v104, 80, v235
	v_add_u32_e32 v105, 81, v235
	v_add_u32_e32 v106, 82, v235
	v_add_u32_e32 v107, 83, v235
	v_add_u32_e32 v109, 96, v235
	v_add_u32_e32 v110, 97, v235
	v_add_u32_e32 v111, 98, v235
	v_add_u32_e32 v112, 99, v235
	v_add_u32_e32 v114, 112, v235
	v_add_u32_e32 v115, 113, v235
	v_add_u32_e32 v116, 114, v235
	v_add_u32_e32 v117, 115, v235
	v_add_u32_e32 v119, 128, v235
	v_add_u32_e32 v120, 129, v235
	v_add_u32_e32 v121, 130, v235
	v_add_u32_e32 v122, 131, v235
	v_add_u32_e32 v124, 144, v235
	v_add_u32_e32 v125, 145, v235
	v_add_u32_e32 v126, 146, v235
	v_add_u32_e32 v127, 147, v235
	s_lshl_b32 s2, s23, 3
	s_add_i32 s2, s2, s19
	s_mov_b32 s3, s89
	s_lshl_b64 s[2:3], s[2:3], 2
	v_mov_b32_e32 v12, v22
	s_add_u32 s2, s48, s2
	s_addc_u32 s3, s49, s3
	v_lshl_add_u64 v[10:11], v[30:31], 1, v[24:25]
	v_cndmask_b32_e64 v16, v195, v12, s[38:39]
	global_load_dword v163, v1, s[2:3] offset:28
	v_add_u32_e32 v17, 0x80, v12
	ds_read_b128 v[12:15], v78
	ds_read_b128 v[30:33], v78 offset:64
	s_waitcnt lgkmcnt(1)
	v_mfma_f32_16x16x32_bf16 v[12:15], v[12:15], v[2:5], 0
	v_sub_u32_e32 v55, v17, v109
	s_or_b32 s88, s88, 0x380
	s_add_i32 s22, s22, s92
	s_waitcnt lgkmcnt(0)
	v_mfma_f32_16x16x32_bf16 v[12:15], v[30:33], v[6:9], v[12:15]
	v_sub_u32_e32 v30, v17, v79
	v_sub_u32_e32 v31, v16, v30
	v_or_b32_e32 v31, v31, v30
	v_and_b32_e32 v30, 0x7f, v30
	v_lshl_add_u32 v30, v30, 2, s97
	ds_read_b32 v30, v30
	v_ashrrev_i32_e32 v31, 31, v31
	v_and_b32_e32 v31, 0xff800000, v31
	s_xor_b64 s[42:43], s[42:43], s[44:45]
	s_cmpk_gt_i32 s22, 0xff
	s_waitcnt lgkmcnt(0)
	v_add_f32_e32 v12, v12, v30
	v_sub_u32_e32 v30, v17, v80
	v_add_f32_e32 v12, v12, v31
	v_sub_u32_e32 v31, v16, v30
	v_or_b32_e32 v31, v31, v30
	v_and_b32_e32 v30, 0x7f, v30
	v_lshl_add_u32 v30, v30, 2, s97
	ds_read_b32 v30, v30
	v_ashrrev_i32_e32 v31, 31, v31
	v_and_b32_e32 v31, 0xff800000, v31
	s_waitcnt lgkmcnt(0)
	v_add_f32_e32 v13, v13, v30
	v_add_f32_e32 v13, v13, v31
	v_sub_u32_e32 v31, v17, v81
	v_sub_u32_e32 v32, v16, v31
	v_or_b32_e32 v32, v32, v31
	v_and_b32_e32 v31, 0x7f, v31
	v_lshl_add_u32 v31, v31, 2, s97
	ds_read_b32 v31, v31
	v_ashrrev_i32_e32 v32, 31, v32
	v_and_b32_e32 v32, 0xff800000, v32
	v_max3_f32 v30, v12, s96, v13
	s_waitcnt lgkmcnt(0)
	v_add_f32_e32 v14, v14, v31
	v_sub_u32_e32 v31, v17, v82
	v_add_f32_e32 v14, v14, v32
	v_sub_u32_e32 v32, v16, v31
	v_or_b32_e32 v32, v32, v31
	v_and_b32_e32 v31, 0x7f, v31
	v_lshl_add_u32 v31, v31, 2, s97
	ds_read_b32 v31, v31
	v_ashrrev_i32_e32 v32, 31, v32
	v_and_b32_e32 v32, 0xff800000, v32
	s_waitcnt lgkmcnt(0)
	v_add_f32_e32 v15, v15, v31
	v_add_f32_e32 v15, v15, v32
	v_max3_f32 v38, v30, v14, v15
	ds_read_b128 v[30:33], v83
	ds_read_b128 v[34:37], v83 offset:64
	s_waitcnt lgkmcnt(1)
	v_mfma_f32_16x16x32_bf16 v[30:33], v[30:33], v[2:5], 0
	s_waitcnt lgkmcnt(0)
	v_mfma_f32_16x16x32_bf16 v[30:33], v[34:37], v[6:9], v[30:33]
	v_sub_u32_e32 v34, v17, v84
	v_sub_u32_e32 v35, v16, v34
	v_or_b32_e32 v35, v35, v34
	v_and_b32_e32 v34, 0x7f, v34
	v_lshl_add_u32 v34, v34, 2, s97
	ds_read_b32 v34, v34
	v_ashrrev_i32_e32 v35, 31, v35
	v_and_b32_e32 v35, 0xff800000, v35
	s_waitcnt lgkmcnt(0)
	v_add_f32_e32 v30, v30, v34
	v_sub_u32_e32 v34, v17, v85
	v_add_f32_e32 v30, v30, v35
	v_sub_u32_e32 v35, v16, v34
	v_or_b32_e32 v35, v35, v34
	v_and_b32_e32 v34, 0x7f, v34
	v_lshl_add_u32 v34, v34, 2, s97
	ds_read_b32 v34, v34
	v_ashrrev_i32_e32 v35, 31, v35
	v_and_b32_e32 v35, 0xff800000, v35
	s_waitcnt lgkmcnt(0)
	v_add_f32_e32 v31, v31, v34
	v_add_f32_e32 v31, v31, v35
	v_sub_u32_e32 v35, v17, v86
	v_sub_u32_e32 v36, v16, v35
	v_or_b32_e32 v36, v36, v35
	v_and_b32_e32 v35, 0x7f, v35
	v_lshl_add_u32 v35, v35, 2, s97
	ds_read_b32 v35, v35
	v_ashrrev_i32_e32 v36, 31, v36
	v_and_b32_e32 v36, 0xff800000, v36
	v_max3_f32 v34, v38, v30, v31
	s_waitcnt lgkmcnt(0)
	v_add_f32_e32 v32, v32, v35
	v_sub_u32_e32 v35, v17, v87
	v_add_f32_e32 v32, v32, v36
	v_sub_u32_e32 v36, v16, v35
	v_or_b32_e32 v36, v36, v35
	v_and_b32_e32 v35, 0x7f, v35
	v_lshl_add_u32 v35, v35, 2, s97
	ds_read_b32 v35, v35
	v_ashrrev_i32_e32 v36, 31, v36
	v_and_b32_e32 v36, 0xff800000, v36
	s_waitcnt lgkmcnt(0)
	v_add_f32_e32 v33, v33, v35
	v_add_f32_e32 v33, v33, v36
	v_max3_f32 v42, v34, v32, v33
	ds_read_b128 v[34:37], v88
	ds_read_b128 v[38:41], v88 offset:64
	s_waitcnt lgkmcnt(1)
	v_mfma_f32_16x16x32_bf16 v[34:37], v[34:37], v[2:5], 0
	s_waitcnt lgkmcnt(0)
	v_mfma_f32_16x16x32_bf16 v[34:37], v[38:41], v[6:9], v[34:37]
	v_sub_u32_e32 v38, v17, v89
	v_sub_u32_e32 v39, v16, v38
	v_or_b32_e32 v39, v39, v38
	v_and_b32_e32 v38, 0x7f, v38
	v_lshl_add_u32 v38, v38, 2, s97
	ds_read_b32 v38, v38
	v_ashrrev_i32_e32 v39, 31, v39
	v_and_b32_e32 v39, 0xff800000, v39
	s_waitcnt lgkmcnt(0)
	v_add_f32_e32 v34, v34, v38
	v_sub_u32_e32 v38, v17, v90
	v_add_f32_e32 v34, v34, v39
	v_sub_u32_e32 v39, v16, v38
	v_or_b32_e32 v39, v39, v38
	v_and_b32_e32 v38, 0x7f, v38
	v_lshl_add_u32 v38, v38, 2, s97
	ds_read_b32 v38, v38
	v_ashrrev_i32_e32 v39, 31, v39
	v_and_b32_e32 v39, 0xff800000, v39
	s_waitcnt lgkmcnt(0)
	v_add_f32_e32 v35, v35, v38
	v_add_f32_e32 v35, v35, v39
	v_sub_u32_e32 v39, v17, v91
	v_sub_u32_e32 v40, v16, v39
	v_or_b32_e32 v40, v40, v39
	v_and_b32_e32 v39, 0x7f, v39
	v_lshl_add_u32 v39, v39, 2, s97
	ds_read_b32 v39, v39
	v_ashrrev_i32_e32 v40, 31, v40
	v_and_b32_e32 v40, 0xff800000, v40
	v_max3_f32 v38, v42, v34, v35
	s_waitcnt lgkmcnt(0)
	v_add_f32_e32 v36, v36, v39
	v_sub_u32_e32 v39, v17, v92
	v_add_f32_e32 v36, v36, v40
	v_sub_u32_e32 v40, v16, v39
	v_or_b32_e32 v40, v40, v39
	v_and_b32_e32 v39, 0x7f, v39
	v_lshl_add_u32 v39, v39, 2, s97
	ds_read_b32 v39, v39
	v_ashrrev_i32_e32 v40, 31, v40
	v_and_b32_e32 v40, 0xff800000, v40
	s_waitcnt lgkmcnt(0)
	v_add_f32_e32 v37, v37, v39
	v_add_f32_e32 v37, v37, v40
	v_max3_f32 v46, v38, v36, v37
	ds_read_b128 v[38:41], v93
	ds_read_b128 v[42:45], v93 offset:64
	s_waitcnt lgkmcnt(1)
	v_mfma_f32_16x16x32_bf16 v[38:41], v[38:41], v[2:5], 0
	s_waitcnt lgkmcnt(0)
	v_mfma_f32_16x16x32_bf16 v[38:41], v[42:45], v[6:9], v[38:41]
	v_sub_u32_e32 v42, v17, v94
	v_sub_u32_e32 v43, v16, v42
	v_or_b32_e32 v43, v43, v42
	v_and_b32_e32 v42, 0x7f, v42
	v_lshl_add_u32 v42, v42, 2, s97
	ds_read_b32 v42, v42
	v_ashrrev_i32_e32 v43, 31, v43
	v_and_b32_e32 v43, 0xff800000, v43
	s_waitcnt lgkmcnt(0)
	v_add_f32_e32 v38, v38, v42
	v_sub_u32_e32 v42, v17, v95
	v_add_f32_e32 v38, v38, v43
	v_sub_u32_e32 v43, v16, v42
	v_or_b32_e32 v43, v43, v42
	v_and_b32_e32 v42, 0x7f, v42
	v_lshl_add_u32 v42, v42, 2, s97
	ds_read_b32 v42, v42
	v_ashrrev_i32_e32 v43, 31, v43
	v_and_b32_e32 v43, 0xff800000, v43
	s_waitcnt lgkmcnt(0)
	v_add_f32_e32 v39, v39, v42
	v_add_f32_e32 v39, v39, v43
	v_sub_u32_e32 v43, v17, v96
	v_sub_u32_e32 v44, v16, v43
	v_or_b32_e32 v44, v44, v43
	v_and_b32_e32 v43, 0x7f, v43
	v_lshl_add_u32 v43, v43, 2, s97
	ds_read_b32 v43, v43
	v_ashrrev_i32_e32 v44, 31, v44
	v_and_b32_e32 v44, 0xff800000, v44
	v_max3_f32 v42, v46, v38, v39
	s_waitcnt lgkmcnt(0)
	v_add_f32_e32 v40, v40, v43
	v_sub_u32_e32 v43, v17, v97
	v_add_f32_e32 v40, v40, v44
	v_sub_u32_e32 v44, v16, v43
	v_or_b32_e32 v44, v44, v43
	v_and_b32_e32 v43, 0x7f, v43
	v_lshl_add_u32 v43, v43, 2, s97
	ds_read_b32 v43, v43
	v_ashrrev_i32_e32 v44, 31, v44
	v_and_b32_e32 v44, 0xff800000, v44
	s_waitcnt lgkmcnt(0)
	v_add_f32_e32 v41, v41, v43
	v_add_f32_e32 v41, v41, v44
	v_max3_f32 v50, v42, v40, v41
	ds_read_b128 v[42:45], v98
	ds_read_b128 v[46:49], v98 offset:64
	s_waitcnt lgkmcnt(1)
	v_mfma_f32_16x16x32_bf16 v[42:45], v[42:45], v[2:5], 0
	s_waitcnt lgkmcnt(0)
	v_mfma_f32_16x16x32_bf16 v[42:45], v[46:49], v[6:9], v[42:45]
	v_sub_u32_e32 v46, v17, v99
	v_sub_u32_e32 v47, v16, v46
	v_or_b32_e32 v47, v47, v46
	v_and_b32_e32 v46, 0x7f, v46
	v_lshl_add_u32 v46, v46, 2, s97
	ds_read_b32 v46, v46
	v_ashrrev_i32_e32 v47, 31, v47
	v_and_b32_e32 v47, 0xff800000, v47
	s_waitcnt lgkmcnt(0)
	v_add_f32_e32 v42, v42, v46
	v_sub_u32_e32 v46, v17, v100
	v_add_f32_e32 v42, v42, v47
	v_sub_u32_e32 v47, v16, v46
	v_or_b32_e32 v47, v47, v46
	v_and_b32_e32 v46, 0x7f, v46
	v_lshl_add_u32 v46, v46, 2, s97
	ds_read_b32 v46, v46
	v_ashrrev_i32_e32 v47, 31, v47
	v_and_b32_e32 v47, 0xff800000, v47
	s_waitcnt lgkmcnt(0)
	v_add_f32_e32 v43, v43, v46
	v_add_f32_e32 v43, v43, v47
	v_sub_u32_e32 v47, v17, v101
	v_sub_u32_e32 v48, v16, v47
	v_or_b32_e32 v48, v48, v47
	v_and_b32_e32 v47, 0x7f, v47
	v_lshl_add_u32 v47, v47, 2, s97
	ds_read_b32 v47, v47
	v_ashrrev_i32_e32 v48, 31, v48
	v_and_b32_e32 v48, 0xff800000, v48
	v_max3_f32 v46, v50, v42, v43
	s_waitcnt lgkmcnt(0)
	v_add_f32_e32 v44, v44, v47
	v_sub_u32_e32 v47, v17, v102
	v_add_f32_e32 v44, v44, v48
	v_sub_u32_e32 v48, v16, v47
	v_or_b32_e32 v48, v48, v47
	v_and_b32_e32 v47, 0x7f, v47
	v_lshl_add_u32 v47, v47, 2, s97
	ds_read_b32 v47, v47
	v_ashrrev_i32_e32 v48, 31, v48
	v_and_b32_e32 v48, 0xff800000, v48
	s_waitcnt lgkmcnt(0)
	v_add_f32_e32 v45, v45, v47
	v_add_f32_e32 v45, v45, v48
	v_max3_f32 v54, v46, v44, v45
	ds_read_b128 v[46:49], v103
	ds_read_b128 v[50:53], v103 offset:64
	s_waitcnt lgkmcnt(1)
	v_mfma_f32_16x16x32_bf16 v[46:49], v[46:49], v[2:5], 0
	s_waitcnt lgkmcnt(0)
	v_mfma_f32_16x16x32_bf16 v[46:49], v[50:53], v[6:9], v[46:49]
	v_sub_u32_e32 v50, v17, v104
	v_sub_u32_e32 v51, v16, v50
	v_or_b32_e32 v51, v51, v50
	v_and_b32_e32 v50, 0x7f, v50
	v_lshl_add_u32 v50, v50, 2, s97
	ds_read_b32 v50, v50
	v_ashrrev_i32_e32 v51, 31, v51
	v_and_b32_e32 v51, 0xff800000, v51
	s_waitcnt lgkmcnt(0)
	v_add_f32_e32 v46, v46, v50
	v_sub_u32_e32 v50, v17, v105
	v_add_f32_e32 v46, v46, v51
	v_sub_u32_e32 v51, v16, v50
	v_or_b32_e32 v51, v51, v50
	v_and_b32_e32 v50, 0x7f, v50
	v_lshl_add_u32 v50, v50, 2, s97
	ds_read_b32 v50, v50
	v_ashrrev_i32_e32 v51, 31, v51
	v_and_b32_e32 v51, 0xff800000, v51
	s_waitcnt lgkmcnt(0)
	v_add_f32_e32 v47, v47, v50
	v_add_f32_e32 v47, v47, v51
	v_sub_u32_e32 v51, v17, v106
	v_sub_u32_e32 v52, v16, v51
	v_or_b32_e32 v52, v52, v51
	v_and_b32_e32 v51, 0x7f, v51
	v_lshl_add_u32 v51, v51, 2, s97
	ds_read_b32 v51, v51
	v_ashrrev_i32_e32 v52, 31, v52
	v_and_b32_e32 v52, 0xff800000, v52
	v_max3_f32 v50, v54, v46, v47
	s_waitcnt lgkmcnt(0)
	v_add_f32_e32 v48, v48, v51
	v_sub_u32_e32 v51, v17, v107
	v_add_f32_e32 v48, v48, v52
	v_sub_u32_e32 v52, v16, v51
	v_or_b32_e32 v52, v52, v51
	v_and_b32_e32 v51, 0x7f, v51
	v_lshl_add_u32 v51, v51, 2, s97
	ds_read_b32 v51, v51
	v_ashrrev_i32_e32 v52, 31, v52
	v_and_b32_e32 v52, 0xff800000, v52
	s_waitcnt lgkmcnt(0)
	v_add_f32_e32 v49, v49, v51
	v_add_f32_e32 v49, v49, v52
	v_max3_f32 v54, v50, v48, v49
	ds_read_b128 v[50:53], v108
	ds_read_b128 v[164:167], v108 offset:64
	s_waitcnt lgkmcnt(1)
	v_mfma_f32_16x16x32_bf16 v[50:53], v[50:53], v[2:5], 0
	s_waitcnt lgkmcnt(0)
	v_mfma_f32_16x16x32_bf16 v[50:53], v[164:167], v[6:9], v[50:53]
	v_sub_u32_e32 v164, v16, v55
	v_or_b32_e32 v164, v164, v55
	v_and_b32_e32 v55, 0x7f, v55
	v_lshl_add_u32 v55, v55, 2, s97
	ds_read_b32 v55, v55
	v_ashrrev_i32_e32 v164, 31, v164
	v_and_b32_e32 v164, 0xff800000, v164
	s_waitcnt lgkmcnt(0)
	v_add_f32_e32 v50, v50, v55
	v_sub_u32_e32 v55, v17, v110
	v_add_f32_e32 v50, v50, v164
	v_sub_u32_e32 v164, v16, v55
	v_or_b32_e32 v164, v164, v55
	v_and_b32_e32 v55, 0x7f, v55
	v_lshl_add_u32 v55, v55, 2, s97
	ds_read_b32 v55, v55
	v_ashrrev_i32_e32 v164, 31, v164
	v_and_b32_e32 v164, 0xff800000, v164
	s_waitcnt lgkmcnt(0)
	v_add_f32_e32 v51, v51, v55
	v_sub_u32_e32 v55, v17, v111
	v_add_f32_e32 v51, v51, v164
	v_sub_u32_e32 v164, v16, v55
	v_or_b32_e32 v164, v164, v55
	v_and_b32_e32 v55, 0x7f, v55
	v_lshl_add_u32 v55, v55, 2, s97
	ds_read_b32 v55, v55
	v_ashrrev_i32_e32 v164, 31, v164
	v_and_b32_e32 v164, 0xff800000, v164
	v_max3_f32 v54, v54, v50, v51
	s_waitcnt lgkmcnt(0)
	v_add_f32_e32 v52, v52, v55
	v_sub_u32_e32 v55, v17, v112
	v_add_f32_e32 v52, v52, v164
	v_sub_u32_e32 v164, v16, v55
	v_or_b32_e32 v164, v164, v55
	v_and_b32_e32 v55, 0x7f, v55
	v_lshl_add_u32 v55, v55, 2, s97
	ds_read_b32 v55, v55
	v_ashrrev_i32_e32 v164, 31, v164
	v_and_b32_e32 v164, 0xff800000, v164
	s_waitcnt lgkmcnt(0)
	v_add_f32_e32 v53, v53, v55
	v_add_f32_e32 v53, v53, v164
	ds_read_b128 v[164:167], v113
	ds_read_b128 v[168:171], v113 offset:64
	v_max3_f32 v172, v54, v52, v53
	v_sub_u32_e32 v54, v17, v114
	s_waitcnt lgkmcnt(1)
	v_mfma_f32_16x16x32_bf16 v[164:167], v[164:167], v[2:5], 0
	v_sub_u32_e32 v55, v16, v54
	v_or_b32_e32 v55, v55, v54
	v_and_b32_e32 v54, 0x7f, v54
	v_lshl_add_u32 v54, v54, 2, s97
	ds_read_b32 v54, v54
	s_waitcnt lgkmcnt(1)
	v_mfma_f32_16x16x32_bf16 v[164:167], v[168:171], v[6:9], v[164:167]
	v_ashrrev_i32_e32 v55, 31, v55
	v_and_b32_e32 v55, 0xff800000, v55
	s_waitcnt lgkmcnt(0)
	s_nop 4
	v_add_f32_e32 v54, v164, v54
	v_add_f32_e32 v54, v54, v55
	v_sub_u32_e32 v55, v17, v115
	v_sub_u32_e32 v164, v16, v55
	v_or_b32_e32 v164, v164, v55
	v_and_b32_e32 v55, 0x7f, v55
	v_lshl_add_u32 v55, v55, 2, s97
	ds_read_b32 v55, v55
	v_ashrrev_i32_e32 v164, 31, v164
	v_and_b32_e32 v164, 0xff800000, v164
	s_waitcnt lgkmcnt(0)
	v_add_f32_e32 v55, v165, v55
	v_add_f32_e32 v55, v55, v164
	v_sub_u32_e32 v164, v17, v116
	v_sub_u32_e32 v165, v16, v164
	v_or_b32_e32 v165, v165, v164
	v_and_b32_e32 v164, 0x7f, v164
	v_lshl_add_u32 v164, v164, 2, s97
	ds_read_b32 v164, v164
	v_ashrrev_i32_e32 v165, 31, v165
	v_and_b32_e32 v165, 0xff800000, v165
	v_max3_f32 v168, v172, v54, v55
	s_waitcnt lgkmcnt(0)
	v_add_f32_e32 v164, v166, v164
	v_add_f32_e32 v164, v164, v165
	v_sub_u32_e32 v165, v17, v117
	v_sub_u32_e32 v166, v16, v165
	v_or_b32_e32 v166, v166, v165
	v_and_b32_e32 v165, 0x7f, v165
	v_lshl_add_u32 v165, v165, 2, s97
	ds_read_b32 v165, v165
	v_ashrrev_i32_e32 v166, 31, v166
	v_and_b32_e32 v166, 0xff800000, v166
	s_waitcnt lgkmcnt(0)
	v_add_f32_e32 v165, v167, v165
	v_add_f32_e32 v165, v165, v166
	v_max3_f32 v174, v168, v164, v165
	ds_read_b128 v[166:169], v118
	ds_read_b128 v[170:173], v118 offset:64
	s_waitcnt lgkmcnt(1)
	v_mfma_f32_16x16x32_bf16 v[166:169], v[166:169], v[2:5], 0
	s_waitcnt lgkmcnt(0)
	v_mfma_f32_16x16x32_bf16 v[166:169], v[170:173], v[6:9], v[166:169]
	v_sub_u32_e32 v170, v17, v119
	v_sub_u32_e32 v171, v16, v170
	v_or_b32_e32 v171, v171, v170
	v_and_b32_e32 v170, 0x7f, v170
	v_lshl_add_u32 v170, v170, 2, s97
	ds_read_b32 v170, v170
	v_ashrrev_i32_e32 v171, 31, v171
	v_and_b32_e32 v171, 0xff800000, v171
	s_waitcnt lgkmcnt(0)
	v_add_f32_e32 v166, v166, v170
	v_sub_u32_e32 v170, v17, v120
	v_add_f32_e32 v166, v166, v171
	v_sub_u32_e32 v171, v16, v170
	v_or_b32_e32 v171, v171, v170
	v_and_b32_e32 v170, 0x7f, v170
	v_lshl_add_u32 v170, v170, 2, s97
	ds_read_b32 v170, v170
	v_ashrrev_i32_e32 v171, 31, v171
	v_and_b32_e32 v171, 0xff800000, v171
	s_waitcnt lgkmcnt(0)
	v_add_f32_e32 v167, v167, v170
	v_add_f32_e32 v167, v167, v171
	v_sub_u32_e32 v171, v17, v121
	v_sub_u32_e32 v172, v16, v171
	v_or_b32_e32 v172, v172, v171
	v_and_b32_e32 v171, 0x7f, v171
	v_lshl_add_u32 v171, v171, 2, s97
	ds_read_b32 v171, v171
	v_ashrrev_i32_e32 v172, 31, v172
	v_and_b32_e32 v172, 0xff800000, v172
	v_max3_f32 v170, v174, v166, v167
	s_waitcnt lgkmcnt(0)
	v_add_f32_e32 v168, v168, v171
	v_sub_u32_e32 v171, v17, v122
	v_add_f32_e32 v168, v168, v172
	v_sub_u32_e32 v172, v16, v171
	v_or_b32_e32 v172, v172, v171
	v_and_b32_e32 v171, 0x7f, v171
	v_lshl_add_u32 v171, v171, 2, s97
	ds_read_b32 v171, v171
	v_ashrrev_i32_e32 v172, 31, v172
	v_and_b32_e32 v172, 0xff800000, v172
	s_waitcnt lgkmcnt(0)
	v_add_f32_e32 v169, v169, v171
	v_add_f32_e32 v169, v169, v172
	v_max3_f32 v178, v170, v168, v169
	ds_read_b128 v[170:173], v123
	ds_read_b128 v[174:177], v123 offset:64
	s_waitcnt lgkmcnt(1)
	v_mfma_f32_16x16x32_bf16 v[2:5], v[170:173], v[2:5], 0
	s_waitcnt lgkmcnt(0)
	v_mfma_f32_16x16x32_bf16 v[2:5], v[174:177], v[6:9], v[2:5]
	v_sub_u32_e32 v6, v17, v124
	v_sub_u32_e32 v7, v16, v6
	v_or_b32_e32 v7, v7, v6
	v_and_b32_e32 v6, 0x7f, v6
	v_lshl_add_u32 v6, v6, 2, s97
	ds_read_b32 v6, v6
	v_ashrrev_i32_e32 v7, 31, v7
	v_and_b32_e32 v7, 0xff800000, v7
	s_waitcnt lgkmcnt(0)
	v_add_f32_e32 v2, v2, v6
	v_add_f32_e32 v170, v2, v7
	v_sub_u32_e32 v2, v17, v125
	v_sub_u32_e32 v6, v16, v2
	v_or_b32_e32 v6, v6, v2
	v_and_b32_e32 v2, 0x7f, v2
	v_lshl_add_u32 v2, v2, 2, s97
	ds_read_b32 v2, v2
	v_ashrrev_i32_e32 v6, 31, v6
	v_and_b32_e32 v6, 0xff800000, v6
	s_waitcnt lgkmcnt(0)
	v_add_f32_e32 v2, v3, v2
	v_sub_u32_e32 v3, v17, v126
	v_add_f32_e32 v171, v2, v6
	v_sub_u32_e32 v6, v16, v3
	v_or_b32_e32 v6, v6, v3
	v_and_b32_e32 v3, 0x7f, v3
	v_lshl_add_u32 v3, v3, 2, s97
	ds_read_b32 v3, v3
	v_ashrrev_i32_e32 v6, 31, v6
	v_and_b32_e32 v6, 0xff800000, v6
	v_max3_f32 v2, v178, v170, v171
	s_waitcnt lgkmcnt(0)
	v_add_f32_e32 v3, v4, v3
	v_add_f32_e32 v172, v3, v6
	v_sub_u32_e32 v3, v17, v127
	v_sub_u32_e32 v4, v16, v3
	v_or_b32_e32 v4, v4, v3
	v_and_b32_e32 v3, 0x7f, v3
	v_lshl_add_u32 v3, v3, 2, s97
	ds_read_b32 v3, v3
	v_ashrrev_i32_e32 v4, 31, v4
	v_and_b32_e32 v4, 0xff800000, v4
	s_waitcnt lgkmcnt(0)
	v_add_f32_e32 v3, v5, v3
	v_add_f32_e32 v173, v3, v4
	v_max3_f32 v2, v2, v172, v173
	ds_swizzle_b32 v3, v2 offset:swizzle(SWAP,16)
	s_waitcnt lgkmcnt(0)
	v_max_f32_e32 v3, v3, v3
	v_max_f32_e32 v2, v2, v3
	ds_bpermute_b32 v3, v19, v2
	s_waitcnt vmcnt(0) lgkmcnt(0)
	v_max3_f32 v174, v2, v3, v163
	v_sub_f32_e32 v2, v12, v174
	v_mul_f32_e32 v2, 0x3fb8aa3b, v2
	v_sub_f32_e32 v3, v13, v174
	v_exp_f32_e32 v2, v2
	v_mul_f32_e32 v3, 0x3fb8aa3b, v3
	v_exp_f32_e32 v3, v3
	v_sub_f32_e32 v7, v30, v174
	v_add_f32_e32 v4, 0, v2
	v_mul_f32_e32 v7, 0x3fb8aa3b, v7
	v_add_f32_e32 v5, v3, v4
	v_sub_f32_e32 v4, v14, v174
	v_mul_f32_e32 v4, 0x3fb8aa3b, v4
	v_exp_f32_e32 v4, v4
	v_exp_f32_e32 v8, v7
	v_sub_f32_e32 v7, v31, v174
	v_mul_f32_e32 v7, 0x3fb8aa3b, v7
	v_add_f32_e32 v6, v4, v5
	v_sub_f32_e32 v5, v15, v174
	v_mul_f32_e32 v5, 0x3fb8aa3b, v5
	v_exp_f32_e32 v5, v5
	v_exp_f32_e32 v9, v7
	v_sub_f32_e32 v7, v32, v174
	v_mul_f32_e32 v7, 0x3fb8aa3b, v7
	v_exp_f32_e32 v16, v7
	v_sub_f32_e32 v7, v33, v174
	v_mul_f32_e32 v7, 0x3fb8aa3b, v7
	v_add_f32_e32 v6, v5, v6
	v_exp_f32_e32 v17, v7
	v_add_f32_e32 v6, v8, v6
	v_add_f32_e32 v6, v9, v6
	v_add_f32_e32 v6, v16, v6
	v_add_f32_e32 v7, v17, v6
	v_sub_f32_e32 v6, v34, v174
	v_mul_f32_e32 v6, 0x3fb8aa3b, v6
	v_exp_f32_e32 v6, v6
	v_sub_f32_e32 v15, v38, v174
	v_mul_f32_e32 v15, 0x3fb8aa3b, v15
	v_exp_f32_e32 v30, v15
	v_add_f32_e32 v12, v6, v7
	v_sub_f32_e32 v7, v35, v174
	v_mul_f32_e32 v7, 0x3fb8aa3b, v7
	v_exp_f32_e32 v7, v7
	v_sub_f32_e32 v15, v39, v174
	v_mul_f32_e32 v15, 0x3fb8aa3b, v15
	v_exp_f32_e32 v31, v15
	v_add_f32_e32 v13, v7, v12
	v_sub_f32_e32 v12, v36, v174
	v_mul_f32_e32 v12, 0x3fb8aa3b, v12
	v_exp_f32_e32 v12, v12
	v_sub_f32_e32 v15, v40, v174
	v_mul_f32_e32 v15, 0x3fb8aa3b, v15
	v_exp_f32_e32 v36, v15
	v_add_f32_e32 v14, v12, v13
	v_sub_f32_e32 v13, v37, v174
	v_mul_f32_e32 v13, 0x3fb8aa3b, v13
	v_exp_f32_e32 v13, v13
	v_sub_f32_e32 v15, v41, v174
	v_mul_f32_e32 v15, 0x3fb8aa3b, v15
	v_exp_f32_e32 v37, v15
	v_add_f32_e32 v14, v13, v14
	v_add_f32_e32 v14, v30, v14
	v_add_f32_e32 v14, v31, v14
	v_add_f32_e32 v14, v36, v14
	v_add_f32_e32 v15, v37, v14
	v_sub_f32_e32 v14, v42, v174
	v_mul_f32_e32 v14, 0x3fb8aa3b, v14
	v_exp_f32_e32 v14, v14
	v_sub_f32_e32 v35, v46, v174
	v_mul_f32_e32 v35, 0x3fb8aa3b, v35
	v_exp_f32_e32 v38, v35
	v_add_f32_e32 v32, v14, v15
	v_sub_f32_e32 v15, v43, v174
	v_mul_f32_e32 v15, 0x3fb8aa3b, v15
	v_exp_f32_e32 v15, v15
	v_sub_f32_e32 v35, v47, v174
	v_mul_f32_e32 v35, 0x3fb8aa3b, v35
	v_exp_f32_e32 v39, v35
	v_add_f32_e32 v33, v15, v32
	v_sub_f32_e32 v32, v44, v174
	v_mul_f32_e32 v32, 0x3fb8aa3b, v32
	v_exp_f32_e32 v32, v32
	v_sub_f32_e32 v35, v48, v174
	v_mul_f32_e32 v35, 0x3fb8aa3b, v35
	v_exp_f32_e32 v44, v35
	v_add_f32_e32 v34, v32, v33
	v_sub_f32_e32 v33, v45, v174
	v_mul_f32_e32 v33, 0x3fb8aa3b, v33
	v_exp_f32_e32 v33, v33
	v_sub_f32_e32 v35, v49, v174
	v_mul_f32_e32 v35, 0x3fb8aa3b, v35
	v_exp_f32_e32 v45, v35
	v_add_f32_e32 v34, v33, v34
	v_add_f32_e32 v34, v38, v34
	v_add_f32_e32 v34, v39, v34
	v_add_f32_e32 v34, v44, v34
	v_add_f32_e32 v35, v45, v34
	v_sub_f32_e32 v34, v50, v174
	v_mul_f32_e32 v34, 0x3fb8aa3b, v34
	v_exp_f32_e32 v34, v34
	v_sub_f32_e32 v43, v54, v174
	v_mul_f32_e32 v43, 0x3fb8aa3b, v43
	v_exp_f32_e32 v46, v43
	v_add_f32_e32 v40, v34, v35
	v_sub_f32_e32 v35, v51, v174
	v_mul_f32_e32 v35, 0x3fb8aa3b, v35
	v_exp_f32_e32 v35, v35
	v_sub_f32_e32 v43, v55, v174
	v_mul_f32_e32 v43, 0x3fb8aa3b, v43
	v_exp_f32_e32 v47, v43
	v_add_f32_e32 v41, v35, v40
	v_sub_f32_e32 v40, v52, v174
	v_mul_f32_e32 v40, 0x3fb8aa3b, v40
	v_exp_f32_e32 v40, v40
	v_sub_f32_e32 v43, v164, v174
	v_mul_f32_e32 v43, 0x3fb8aa3b, v43
	v_exp_f32_e32 v50, v43
	v_add_f32_e32 v42, v40, v41
	v_sub_f32_e32 v41, v53, v174
	v_mul_f32_e32 v41, 0x3fb8aa3b, v41
	v_exp_f32_e32 v41, v41
	v_sub_f32_e32 v43, v165, v174
	v_mul_f32_e32 v43, 0x3fb8aa3b, v43
	v_exp_f32_e32 v51, v43
	v_add_f32_e32 v42, v41, v42
	v_add_f32_e32 v42, v46, v42
	v_add_f32_e32 v42, v47, v42
	v_add_f32_e32 v42, v50, v42
	v_add_f32_e32 v43, v51, v42
	v_sub_f32_e32 v42, v166, v174
	v_mul_f32_e32 v42, 0x3fb8aa3b, v42
	v_exp_f32_e32 v42, v42
	v_sub_f32_e32 v163, v163, v174
	v_mul_f32_e32 v163, 0x3fb8aa3b, v163
	v_exp_f32_e32 v163, v163
	v_add_f32_e32 v48, v42, v43
	v_sub_f32_e32 v43, v167, v174
	v_mul_f32_e32 v43, 0x3fb8aa3b, v43
	v_exp_f32_e32 v43, v43
	s_nop 0
	v_add_f32_e32 v49, v43, v48
	v_sub_f32_e32 v48, v168, v174
	v_mul_f32_e32 v48, 0x3fb8aa3b, v48
	v_exp_f32_e32 v48, v48
	s_nop 0
	v_add_f32_e32 v52, v48, v49
	v_sub_f32_e32 v49, v169, v174
	v_mul_f32_e32 v49, 0x3fb8aa3b, v49
	v_exp_f32_e32 v49, v49
	s_nop 0
	v_add_f32_e32 v53, v49, v52
	v_sub_f32_e32 v52, v170, v174
	v_mul_f32_e32 v52, 0x3fb8aa3b, v52
	v_exp_f32_e32 v52, v52
	s_nop 0
	v_add_f32_e32 v54, v52, v53
	v_sub_f32_e32 v53, v171, v174
	v_mul_f32_e32 v53, 0x3fb8aa3b, v53
	v_exp_f32_e32 v53, v53
	s_nop 0
	v_add_f32_e32 v55, v53, v54
	v_sub_f32_e32 v54, v172, v174
	v_mul_f32_e32 v54, 0x3fb8aa3b, v54
	v_exp_f32_e32 v54, v54
	s_nop 0
	v_add_f32_e32 v164, v54, v55
	v_sub_f32_e32 v55, v173, v174
	v_mul_f32_e32 v55, 0x3fb8aa3b, v55
	v_exp_f32_e32 v55, v55
	s_nop 0
	v_add_f32_e32 v164, v55, v164
	ds_swizzle_b32 v165, v164 offset:swizzle(SWAP,16)
	s_waitcnt lgkmcnt(0)
	v_add_f32_e32 v164, v164, v165
	ds_bpermute_b32 v165, v19, v164
	s_waitcnt lgkmcnt(0)
	v_add_f32_e32 v164, v164, v165
	v_add_f32_e32 v163, v163, v164
	v_div_scale_f32 v164, s[2:3], v163, v163, 1.0
	v_rcp_f32_e32 v165, v164
	s_nop 0
	v_fma_f32 v166, -v164, v165, 1.0
	v_fmac_f32_e32 v165, v166, v165
	v_div_scale_f32 v166, vcc, 1.0, v163, 1.0
	v_mul_f32_e32 v167, v166, v165
	v_fma_f32 v168, -v164, v167, v166
	v_fmac_f32_e32 v167, v168, v165
	v_fma_f32 v164, -v164, v167, v166
	v_div_fmas_f32 v164, v164, v165, v167
	v_div_fixup_f32 v180, v164, v163, 1.0
	v_pk_mul_f32 v[4:5], v[4:5], v[180:181] op_sel_hi:[1,0]
	v_pk_mul_f32 v[2:3], v[2:3], v[180:181] op_sel_hi:[1,0]
	v_pk_mul_f32 v[16:17], v[16:17], v[180:181] op_sel_hi:[1,0]
	v_pk_mul_f32 v[8:9], v[8:9], v[180:181] op_sel_hi:[1,0]
	v_cvt_pk_bf16_f32 v2, v2, v3
	v_cvt_pk_bf16_f32 v3, v4, v5
	v_pk_mul_f32 v[6:7], v[6:7], v[180:181] op_sel_hi:[1,0]
	v_cvt_pk_bf16_f32 v4, v8, v9
	v_cvt_pk_bf16_f32 v5, v16, v17
	ds_read2_b64 v[164:167], v137 offset1:4
	ds_read2_b64 v[168:171], v138 offset0:32 offset1:36
	ds_read2_b64 v[172:175], v139 offset0:64 offset1:68
	ds_read2_b64 v[176:179], v140 offset0:96 offset1:100
	v_pk_mul_f32 v[8:9], v[12:13], v[180:181] op_sel_hi:[1,0]
	s_waitcnt lgkmcnt(3)
	v_mfma_f32_16x16x32_bf16 v[164:167], v[164:167], v[2:5], 0
	v_mul_f32_e64 v12, v36, v180
	v_mul_f32_e64 v13, v37, v180
	v_pk_mul_f32 v[16:17], v[30:31], v[180:181] op_sel_hi:[1,0]
	v_cvt_pk_bf16_f32 v6, v6, v7
	s_waitcnt lgkmcnt(2)
	v_mfma_f32_16x16x32_bf16 v[168:171], v[168:171], v[2:5], 0
	v_cvt_pk_bf16_f32 v7, v8, v9
	v_cvt_pk_bf16_f32 v8, v16, v17
	v_cvt_pk_bf16_f32 v9, v12, v13
	s_waitcnt lgkmcnt(1)
	v_mfma_f32_16x16x32_bf16 v[172:175], v[172:175], v[2:5], 0
	v_mul_f32_e64 v12, v44, v180
	v_mul_f32_e64 v13, v45, v180
	v_pk_mul_f32 v[16:17], v[50:51], v[180:181] op_sel_hi:[1,0]
	s_waitcnt lgkmcnt(0)
	v_mfma_f32_16x16x32_bf16 v[2:5], v[176:179], v[2:5], 0
	ds_read2_b64 v[176:179], v58 offset1:4
	s_waitcnt lgkmcnt(0)
	v_mfma_f32_16x16x32_bf16 v[164:167], v[176:179], v[6:9], v[164:167]
	ds_read2_b64 v[176:179], v59 offset0:32 offset1:36
	s_waitcnt lgkmcnt(0)
	v_mfma_f32_16x16x32_bf16 v[168:171], v[176:179], v[6:9], v[168:171]
	ds_read2_b64 v[176:179], v60 offset0:64 offset1:68
	ds_read2_b64 v[58:61], v61 offset0:96 offset1:100
	s_waitcnt lgkmcnt(1)
	v_mfma_f32_16x16x32_bf16 v[172:175], v[176:179], v[6:9], v[172:175]
	s_waitcnt lgkmcnt(0)
	v_mfma_f32_16x16x32_bf16 v[2:5], v[58:61], v[6:9], v[2:5]
	v_mul_f32_e64 v8, v32, v180
	v_mul_f32_e64 v9, v33, v180
	v_pk_mul_f32 v[6:7], v[14:15], v[180:181] op_sel_hi:[1,0]
	v_pk_mul_f32 v[14:15], v[38:39], v[180:181] op_sel_hi:[1,0]
	v_cvt_pk_bf16_f32 v6, v6, v7
	v_cvt_pk_bf16_f32 v7, v8, v9
	s_nop 0
	v_cvt_pk_bf16_f32 v8, v14, v15
	v_cvt_pk_bf16_f32 v9, v12, v13
	ds_read2_b64 v[12:15], v56 offset1:4
	ds_read2_b64 v[30:33], v57 offset0:32 offset1:36
	ds_read2_b64 v[36:39], v62 offset0:64 offset1:68
	ds_read2_b64 v[56:59], v63 offset0:96 offset1:100
	s_waitcnt lgkmcnt(3)
	v_mfma_f32_16x16x32_bf16 v[12:15], v[12:15], v[6:9], v[164:167]
	s_waitcnt lgkmcnt(2)
	v_mfma_f32_16x16x32_bf16 v[30:33], v[30:33], v[6:9], v[168:171]
	s_waitcnt lgkmcnt(1)
	v_mfma_f32_16x16x32_bf16 v[36:39], v[36:39], v[6:9], v[172:175]
	s_waitcnt lgkmcnt(0)
	v_mfma_f32_16x16x32_bf16 v[2:5], v[56:59], v[6:9], v[2:5]
	v_mul_f32_e64 v8, v40, v180
	v_mul_f32_e64 v9, v41, v180
	v_pk_mul_f32 v[6:7], v[34:35], v[180:181] op_sel_hi:[1,0]
	v_pk_mul_f32 v[34:35], v[46:47], v[180:181] op_sel_hi:[1,0]
	v_cvt_pk_bf16_f32 v6, v6, v7
	v_cvt_pk_bf16_f32 v7, v8, v9
	s_nop 0
	v_cvt_pk_bf16_f32 v8, v34, v35
	v_cvt_pk_bf16_f32 v9, v16, v17
	ds_read2_b64 v[44:47], v64 offset1:4
	s_waitcnt lgkmcnt(0)
	v_mfma_f32_16x16x32_bf16 v[12:15], v[44:47], v[6:9], v[12:15]
	ds_read2_b64 v[44:47], v65 offset0:32 offset1:36
	v_pk_mul_f32 v[16:17], v[54:55], v[180:181] op_sel_hi:[1,0]
	s_waitcnt lgkmcnt(0)
	v_mfma_f32_16x16x32_bf16 v[30:33], v[44:47], v[6:9], v[30:33]
	ds_read2_b64 v[44:47], v141 offset0:64 offset1:68
	s_waitcnt lgkmcnt(0)
	v_mfma_f32_16x16x32_bf16 v[34:37], v[44:47], v[6:9], v[36:39]
	s_nop 2
	ds_read2_b64 v[38:41], v142 offset0:96 offset1:100
	s_waitcnt lgkmcnt(0)
	v_mfma_f32_16x16x32_bf16 v[2:5], v[38:41], v[6:9], v[2:5]
	v_mul_f32_e64 v8, v48, v180
	v_mul_f32_e64 v9, v49, v180
	v_pk_mul_f32 v[6:7], v[42:43], v[180:181] op_sel_hi:[1,0]
	v_pk_mul_f32 v[38:39], v[52:53], v[180:181] op_sel_hi:[1,0]
	v_cvt_pk_bf16_f32 v6, v6, v7
	v_cvt_pk_bf16_f32 v7, v8, v9
	s_nop 0
	v_cvt_pk_bf16_f32 v8, v38, v39
	v_cvt_pk_bf16_f32 v9, v16, v17
	ds_read2_b64 v[38:41], v143 offset1:4
	s_waitcnt lgkmcnt(0)
	v_mfma_f32_16x16x32_bf16 v[12:15], v[38:41], v[6:9], v[12:15]
	ds_read2_b64 v[38:41], v144 offset0:32 offset1:36
	s_waitcnt lgkmcnt(0)
	v_mfma_f32_16x16x32_bf16 v[30:33], v[38:41], v[6:9], v[30:33]
	ds_read2_b64 v[38:41], v145 offset0:64 offset1:68
	s_waitcnt lgkmcnt(0)
	v_mfma_f32_16x16x32_bf16 v[34:37], v[38:41], v[6:9], v[34:37]
	ds_read2_b64 v[38:41], v162 offset0:96 offset1:100
	s_waitcnt lgkmcnt(0)
	v_mfma_f32_16x16x32_bf16 v[2:5], v[38:41], v[6:9], v[2:5]
	v_lshl_add_u64 v[6:7], v[10:11], 0, s[88:89]
	v_cvt_pk_bf16_f32 v8, v12, v13
	v_cvt_pk_bf16_f32 v9, v14, v15
	global_store_dwordx2 v[6:7], v[8:9], off
	v_cvt_pk_bf16_f32 v8, v30, v31
	v_cvt_pk_bf16_f32 v9, v32, v33
	global_store_dwordx2 v[6:7], v[8:9], off offset:32
	v_cvt_pk_bf16_f32 v8, v34, v35
	v_cvt_pk_bf16_f32 v9, v36, v37
	global_store_dwordx2 v[6:7], v[8:9], off offset:64
	v_cvt_pk_bf16_f32 v2, v2, v3
	v_cvt_pk_bf16_f32 v3, v4, v5
	s_nop 3
	global_store_dwordx2 v[6:7], v[2:3], off offset:96
	s_cbranch_scc0 .LBB0_115
